# v21 + K-loop phases: merged the two pre-barrier waits into one s_waitcnt and dropped the redundant post-barrier lgkmcnt(0) (8 bytes per site, 24 sites)
# baseline (speedup 1.0000x reference)
; #define PG8_STAGE(bufoff, gbase, voff) do { _Pragma("unroll") for (int _i = 0; _i < 2; ++_i) \
;         __builtin_amdgcn_global_load_lds((const unsigned*)((const char*)(gbase) + (voff)[_i]), (PG8_LAS unsigned*)(lds + (bufoff) + ldsw + _i * 8192), 16, 0, 0); } while (0)
; #define PG8_LDA(dst, b, h) do { _Pragma("unroll") for (int m = 0; m < 4; ++m) _Pragma("unroll") for (int k = 0; k < 2; ++k) dst[m][k] = *(const PG8_LAS bf16x8*)(lds + PG8_SA(b, h) + aoff + m * 2048 + k * 1024); } while (0)
; #define PG8_LDB(dst, b, h) do { _Pragma("unroll") for (int n = 0; n < 2; ++n) _Pragma("unroll") for (int k = 0; k < 2; ++k) dst[n][k] = *(const PG8_LAS bf16x8*)(lds + PG8_SB(b, h) + boff + n * 2048 + k * 1024); } while (0)
; #define PG8_MMA(ai, bj, At, Bt) do { __builtin_amdgcn_s_setprio(1); _Pragma("unroll") for (int m = 0; m < 4; ++m) _Pragma("unroll") for (int n = 0; n < 2; ++n) _Pragma("unroll") for (int k = 0; k < 2; ++k) \
;         acc[ai][bj][m][n] = __builtin_amdgcn_mfma_f32_16x16x32_bf16(Bt[n][k], At[m][k], acc[ai][bj][m][n], 0, 0, 0); __builtin_amdgcn_s_setprio(0); } while (0)
; #define PG8_WAIT_V(n) asm volatile("s_waitcnt vmcnt(" #n ")" ::: "memory")
; #define PG8_BAR __builtin_amdgcn_s_barrier()
; template <class Epi, class Sched, bool ALIGN_EPI = false, bool SP2 = false>
; __device__ __forceinline__ void gemm_phase(PG8_LAS unsigned char* lds, const Gemm g, const Sched& S, const Epi& E, int tid_in) {
;     ...
;         for (int t = 0; t < nt; t += 2) {
;             const bool last = (t == nt - 2);
;             const char* a1 = cA + (size_t)(t + 1) * kstep;
;             const char* a2 = last ? nA : cA + (size_t)(t + 2) * kstep; const char* b2 = last ? nB : cB + (size_t)(t + 2) * kstep;
;             const char* a3 = a2 + kstep; const char* b3 = b2 + kstep;
;             if (last && has_next) S.a_ready(nxt);
;             if constexpr (SP2) {
;             PG8_LDB(B0, 0, 0); PG8_LDB(B1, 0, 1); PG8_SCHED; PG8_LDA(At, 0, 0); PG8_STAGE(PG8_SA(1, 1), a1 + hstep, voffA);
;             PG8_WAIT_V(8); PG8_WAIT_L(0); PG8_BAR; PG8_MMA(0, 0, At, B0); PG8_MMA(0, 1, At, B1); PG8_BAR; PG8_SCHED;
;             PG8_LDA(At, 0, 1); PG8_STAGE(PG8_SB(0, 0), b2, voffB); PG8_STAGE(PG8_SB(0, 1), b2 + hstep, voffB); PG8_STAGE(PG8_SA(0, 0), a2, voffA);
;             PG8_WAIT_V(8); PG8_WAIT_L(0); PG8_BAR; PG8_MMA(1, 0, At, B0); PG8_MMA(1, 1, At, B1); PG8_BAR; PG8_SCHED;
.LBB0_198:
	s_add_u32 s4, s2, 0xfffc0080
	s_addc_u32 s5, s3, -1
	s_add_i32 s43, 0, 0x10000
	s_cmp_eq_u32 s42, 12
	s_cselect_b32 s9, s0, s5
	s_cselect_b32 s8, s1, s4
	v_add_u32_e32 v80, s43, v237
	s_cselect_b32 s5, s38, s41
	s_cselect_b32 s4, s39, s40
	s_add_i32 s46, 0, 0x14000
	ds_read_b128 v[130:133], v80
	ds_read_b128 v[134:137], v80 offset:1024
	ds_read_b128 v[138:141], v80 offset:2048
	ds_read_b128 v[142:145], v80 offset:3072
	v_add_u32_e32 v80, s46, v237
	ds_read_b128 v[146:149], v80
	ds_read_b128 v[150:153], v80 offset:1024
	ds_read_b128 v[154:157], v80 offset:2048
	ds_read_b128 v[172:175], v80 offset:3072
	v_lshl_add_u64 v[158:159], s[2:3], 0, v[168:169]
	s_add_i32 m0, s17, 0xc000
	ds_read_b128 v[176:179], v238
	ds_read_b128 v[180:183], v238 offset:1024
	ds_read_b128 v[190:193], v238 offset:2048
	ds_read_b128 v[194:197], v238 offset:3072
	ds_read_b128 v[198:201], v238 offset:4096
	ds_read_b128 v[202:205], v238 offset:5120
	ds_read_b128 v[206:209], v238 offset:6144
	ds_read_b128 v[210:213], v238 offset:7168
	global_load_lds_dwordx4 v[158:159], off
	v_lshl_add_u64 v[158:159], s[2:3], 0, v[170:171]
	s_add_i32 m0, s17, 0xe000
	s_nop 0
	global_load_lds_dwordx4 v[158:159], off
	s_waitcnt vmcnt(8) lgkmcnt(0)
	s_barrier
	s_setprio 1
	v_mfma_f32_16x16x32_bf16 v[122:125], v[130:133], v[176:179], v[122:125]
	v_mfma_f32_16x16x32_bf16 v[126:129], v[138:141], v[176:179], v[126:129]
	v_mfma_f32_16x16x32_bf16 v[114:117], v[130:133], v[190:193], v[114:117]
	v_mfma_f32_16x16x32_bf16 v[118:121], v[138:141], v[190:193], v[118:121]
	v_mfma_f32_16x16x32_bf16 v[106:109], v[130:133], v[198:201], v[106:109]
	v_mfma_f32_16x16x32_bf16 v[110:113], v[138:141], v[198:201], v[110:113]
	v_mfma_f32_16x16x32_bf16 v[98:101], v[130:133], v[206:209], v[98:101]
	v_mfma_f32_16x16x32_bf16 v[102:105], v[138:141], v[206:209], v[102:105]
	v_mfma_f32_16x16x32_bf16 v[122:125], v[134:137], v[180:183], v[122:125]
	v_mfma_f32_16x16x32_bf16 v[126:129], v[142:145], v[180:183], v[126:129]
	v_mfma_f32_16x16x32_bf16 v[114:117], v[134:137], v[194:197], v[114:117]
	v_mfma_f32_16x16x32_bf16 v[118:121], v[142:145], v[194:197], v[118:121]
	v_mfma_f32_16x16x32_bf16 v[106:109], v[134:137], v[202:205], v[106:109]
	v_mfma_f32_16x16x32_bf16 v[110:113], v[142:145], v[202:205], v[110:113]
	v_mfma_f32_16x16x32_bf16 v[98:101], v[134:137], v[210:213], v[98:101]
	v_mfma_f32_16x16x32_bf16 v[102:105], v[142:145], v[210:213], v[102:105]
	v_mfma_f32_16x16x32_bf16 v[60:63], v[146:149], v[176:179], v[60:63]
	v_mfma_f32_16x16x32_bf16 v[56:59], v[154:157], v[176:179], v[56:59]
	v_mfma_f32_16x16x32_bf16 v[52:55], v[146:149], v[190:193], v[52:55]
	v_mfma_f32_16x16x32_bf16 v[48:51], v[154:157], v[190:193], v[48:51]
	v_mfma_f32_16x16x32_bf16 v[44:47], v[146:149], v[198:201], v[44:47]
	v_mfma_f32_16x16x32_bf16 v[40:43], v[154:157], v[198:201], v[40:43]
	v_mfma_f32_16x16x32_bf16 v[36:39], v[146:149], v[206:209], v[36:39]
	v_mfma_f32_16x16x32_bf16 v[32:35], v[154:157], v[206:209], v[32:35]
	v_mfma_f32_16x16x32_bf16 v[60:63], v[150:153], v[180:183], v[60:63]
	v_mfma_f32_16x16x32_bf16 v[56:59], v[172:175], v[180:183], v[56:59]
	v_mfma_f32_16x16x32_bf16 v[52:55], v[150:153], v[194:197], v[52:55]
	v_mfma_f32_16x16x32_bf16 v[48:51], v[172:175], v[194:197], v[48:51]
	v_mfma_f32_16x16x32_bf16 v[44:47], v[150:153], v[202:205], v[44:47]
	v_mfma_f32_16x16x32_bf16 v[40:43], v[172:175], v[202:205], v[40:43]
	v_mfma_f32_16x16x32_bf16 v[36:39], v[150:153], v[210:213], v[36:39]
	v_mfma_f32_16x16x32_bf16 v[32:35], v[172:175], v[210:213], v[32:35]
	s_setprio 0
	s_barrier
	s_add_i32 s43, s43, s14
	v_lshl_add_u64 v[158:159], s[4:5], 0, v[162:163]
	s_mov_b32 m0, s43
	ds_read_b128 v[176:179], v238 offset:16384
	ds_read_b128 v[180:183], v238 offset:17408
	ds_read_b128 v[190:193], v238 offset:18432
	ds_read_b128 v[194:197], v238 offset:19456
	ds_read_b128 v[198:201], v238 offset:20480
	ds_read_b128 v[202:205], v238 offset:21504
	ds_read_b128 v[206:209], v238 offset:22528
	ds_read_b128 v[210:213], v238 offset:23552
	global_load_lds_dwordx4 v[158:159], off
	s_add_i32 m0, s43, 0x2000
	s_add_u32 s44, s4, 0x40000
	v_lshl_add_u64 v[184:185], s[4:5], 0, v[166:167]
	s_addc_u32 s45, s5, 0
	s_add_i32 s43, s46, s14
	global_load_lds_dwordx4 v[184:185], off
	v_lshl_add_u64 v[186:187], s[44:45], 0, v[162:163]
	s_mov_b32 m0, s43
	v_lshl_add_u64 v[188:189], s[8:9], 0, v[164:165]
	global_load_lds_dwordx4 v[186:187], off
	v_lshl_add_u64 v[186:187], s[44:45], 0, v[166:167]
	s_add_i32 m0, s43, 0x2000
	s_nop 0
	global_load_lds_dwordx4 v[186:187], off
	v_lshl_add_u64 v[186:187], s[8:9], 0, v[160:161]
	s_mov_b32 m0, s17
	s_nop 0
	global_load_lds_dwordx4 v[186:187], off
	s_mov_b32 m0, s18
	s_nop 0
	global_load_lds_dwordx4 v[188:189], off
	s_waitcnt vmcnt(8) lgkmcnt(0)
	s_barrier
; #define PG8_STAGE(bufoff, gbase, voff) do { _Pragma("unroll") for (int _i = 0; _i < 2; ++_i) \
;         __builtin_amdgcn_global_load_lds((const unsigned*)((const char*)(gbase) + (voff)[_i]), (PG8_LAS unsigned*)(lds + (bufoff) + ldsw + _i * 8192), 16, 0, 0); } while (0)
; #define PG8_LDA(dst, b, h) do { _Pragma("unroll") for (int m = 0; m < 4; ++m) _Pragma("unroll") for (int k = 0; k < 2; ++k) dst[m][k] = *(const PG8_LAS bf16x8*)(lds + PG8_SA(b, h) + aoff + m * 2048 + k * 1024); } while (0)
; #define PG8_LDB(dst, b, h) do { _Pragma("unroll") for (int n = 0; n < 2; ++n) _Pragma("unroll") for (int k = 0; k < 2; ++k) dst[n][k] = *(const PG8_LAS bf16x8*)(lds + PG8_SB(b, h) + boff + n * 2048 + k * 1024); } while (0)
; #define PG8_MMA(ai, bj, At, Bt) do { __builtin_amdgcn_s_setprio(1); _Pragma("unroll") for (int m = 0; m < 4; ++m) _Pragma("unroll") for (int n = 0; n < 2; ++n) _Pragma("unroll") for (int k = 0; k < 2; ++k) \
;         acc[ai][bj][m][n] = __builtin_amdgcn_mfma_f32_16x16x32_bf16(Bt[n][k], At[m][k], acc[ai][bj][m][n], 0, 0, 0); __builtin_amdgcn_s_setprio(0); } while (0)
; #define PG8_WAIT_V(n) asm volatile("s_waitcnt vmcnt(" #n ")" ::: "memory")
; #define PG8_WAIT_L(n) asm volatile("s_waitcnt lgkmcnt(" #n ")" ::: "memory")
; #define PG8_BAR __builtin_amdgcn_s_barrier()
; #define PG8_SCHED __builtin_amdgcn_sched_barrier(0)
; template <class Epi, class Sched, bool ALIGN_EPI = false, bool SP2 = false>
; __device__ __forceinline__ void gemm_phase(PG8_LAS unsigned char* lds, const Gemm g, const Sched& S, const Epi& E, int tid_in) {
;     ...
;             PG8_WAIT_V(8); PG8_WAIT_L(0); PG8_BAR; PG8_MMA(1, 0, At, B0); PG8_MMA(1, 1, At, B1); PG8_BAR; PG8_SCHED;
;             PG8_LDB(B0, 1, 0); PG8_LDB(B1, 1, 1); PG8_SCHED; PG8_LDA(At, 1, 0); PG8_STAGE(PG8_SA(0, 1), a2 + hstep, voffA);
;             PG8_WAIT_V(8); PG8_WAIT_L(0); PG8_BAR; PG8_MMA(0, 0, At, B0); PG8_MMA(0, 1, At, B1); PG8_BAR; PG8_SCHED;
	s_setprio 1
	v_mfma_f32_16x16x32_bf16 v[90:93], v[130:133], v[176:179], v[90:93]
	v_mfma_f32_16x16x32_bf16 v[94:97], v[138:141], v[176:179], v[94:97]
	v_mfma_f32_16x16x32_bf16 v[82:85], v[130:133], v[190:193], v[82:85]
	v_mfma_f32_16x16x32_bf16 v[86:89], v[138:141], v[190:193], v[86:89]
	v_mfma_f32_16x16x32_bf16 v[72:75], v[130:133], v[198:201], v[72:75]
	v_mfma_f32_16x16x32_bf16 v[76:79], v[138:141], v[198:201], v[76:79]
	v_mfma_f32_16x16x32_bf16 v[64:67], v[130:133], v[206:209], v[64:67]
	v_mfma_f32_16x16x32_bf16 v[68:71], v[138:141], v[206:209], v[68:71]
	v_mfma_f32_16x16x32_bf16 v[90:93], v[134:137], v[180:183], v[90:93]
	v_mfma_f32_16x16x32_bf16 v[94:97], v[142:145], v[180:183], v[94:97]
	v_mfma_f32_16x16x32_bf16 v[82:85], v[134:137], v[194:197], v[82:85]
	v_mfma_f32_16x16x32_bf16 v[86:89], v[142:145], v[194:197], v[86:89]
	v_mfma_f32_16x16x32_bf16 v[72:75], v[134:137], v[202:205], v[72:75]
	v_mfma_f32_16x16x32_bf16 v[76:79], v[142:145], v[202:205], v[76:79]
	v_mfma_f32_16x16x32_bf16 v[64:67], v[134:137], v[210:213], v[64:67]
	v_mfma_f32_16x16x32_bf16 v[68:71], v[142:145], v[210:213], v[68:71]
	v_mfma_f32_16x16x32_bf16 v[28:31], v[146:149], v[176:179], v[28:31]
	v_mfma_f32_16x16x32_bf16 v[24:27], v[154:157], v[176:179], v[24:27]
	v_mfma_f32_16x16x32_bf16 v[20:23], v[146:149], v[190:193], v[20:23]
	v_mfma_f32_16x16x32_bf16 v[16:19], v[154:157], v[190:193], v[16:19]
	v_mfma_f32_16x16x32_bf16 v[12:15], v[146:149], v[198:201], v[12:15]
	v_mfma_f32_16x16x32_bf16 v[8:11], v[154:157], v[198:201], v[8:11]
	v_mfma_f32_16x16x32_bf16 v[4:7], v[146:149], v[206:209], v[4:7]
	v_mfma_f32_16x16x32_bf16 v[0:3], v[154:157], v[206:209], v[0:3]
	v_mfma_f32_16x16x32_bf16 v[28:31], v[150:153], v[180:183], v[28:31]
	v_mfma_f32_16x16x32_bf16 v[24:27], v[172:175], v[180:183], v[24:27]
	v_mfma_f32_16x16x32_bf16 v[20:23], v[150:153], v[194:197], v[20:23]
	v_mfma_f32_16x16x32_bf16 v[16:19], v[172:175], v[194:197], v[16:19]
	v_mfma_f32_16x16x32_bf16 v[12:15], v[150:153], v[202:205], v[12:15]
	v_mfma_f32_16x16x32_bf16 v[8:11], v[172:175], v[202:205], v[8:11]
	v_mfma_f32_16x16x32_bf16 v[4:7], v[150:153], v[210:213], v[4:7]
	v_mfma_f32_16x16x32_bf16 v[0:3], v[172:175], v[210:213], v[0:3]
	s_setprio 0
	s_barrier
	s_add_i32 s43, 0, 0x18000
	v_add_u32_e32 v80, s43, v237
	s_add_i32 s44, 0, 0x1c000
	ds_read_b128 v[130:133], v80
	ds_read_b128 v[134:137], v80 offset:1024
	ds_read_b128 v[138:141], v80 offset:2048
	ds_read_b128 v[142:145], v80 offset:3072
	v_add_u32_e32 v80, s44, v237
	ds_read_b128 v[146:149], v80
	ds_read_b128 v[150:153], v80 offset:1024
	ds_read_b128 v[154:157], v80 offset:2048
	ds_read_b128 v[172:175], v80 offset:3072
	s_add_u32 s8, s8, 0x40000
	s_addc_u32 s9, s9, 0
	s_mov_b32 m0, s19
	v_lshl_add_u64 v[214:215], s[8:9], 0, v[160:161]
	ds_read_b128 v[176:179], v238 offset:32768
	ds_read_b128 v[180:183], v238 offset:33792
	ds_read_b128 v[190:193], v238 offset:34816
	ds_read_b128 v[194:197], v238 offset:35840
	ds_read_b128 v[198:201], v238 offset:36864
	ds_read_b128 v[202:205], v238 offset:37888
	ds_read_b128 v[206:209], v238 offset:38912
	ds_read_b128 v[210:213], v238 offset:39936
	global_load_lds_dwordx4 v[214:215], off
	v_lshl_add_u64 v[214:215], s[8:9], 0, v[164:165]
	s_mov_b32 m0, s68
	s_nop 0
	global_load_lds_dwordx4 v[214:215], off
	s_waitcnt vmcnt(8) lgkmcnt(0)
	s_barrier
	s_setprio 1
	v_mfma_f32_16x16x32_bf16 v[122:125], v[130:133], v[176:179], v[122:125]
	v_mfma_f32_16x16x32_bf16 v[126:129], v[138:141], v[176:179], v[126:129]
	v_mfma_f32_16x16x32_bf16 v[114:117], v[130:133], v[190:193], v[114:117]
	v_mfma_f32_16x16x32_bf16 v[118:121], v[138:141], v[190:193], v[118:121]
	v_mfma_f32_16x16x32_bf16 v[106:109], v[130:133], v[198:201], v[106:109]
	v_mfma_f32_16x16x32_bf16 v[110:113], v[138:141], v[198:201], v[110:113]
	v_mfma_f32_16x16x32_bf16 v[98:101], v[130:133], v[206:209], v[98:101]
	v_mfma_f32_16x16x32_bf16 v[102:105], v[138:141], v[206:209], v[102:105]
	v_mfma_f32_16x16x32_bf16 v[122:125], v[134:137], v[180:183], v[122:125]
	v_mfma_f32_16x16x32_bf16 v[126:129], v[142:145], v[180:183], v[126:129]
	v_mfma_f32_16x16x32_bf16 v[114:117], v[134:137], v[194:197], v[114:117]
	v_mfma_f32_16x16x32_bf16 v[118:121], v[142:145], v[194:197], v[118:121]
	v_mfma_f32_16x16x32_bf16 v[106:109], v[134:137], v[202:205], v[106:109]
	v_mfma_f32_16x16x32_bf16 v[110:113], v[142:145], v[202:205], v[110:113]
	v_mfma_f32_16x16x32_bf16 v[98:101], v[134:137], v[210:213], v[98:101]
	v_mfma_f32_16x16x32_bf16 v[102:105], v[142:145], v[210:213], v[102:105]
	v_mfma_f32_16x16x32_bf16 v[60:63], v[146:149], v[176:179], v[60:63]
	v_mfma_f32_16x16x32_bf16 v[56:59], v[154:157], v[176:179], v[56:59]
	v_mfma_f32_16x16x32_bf16 v[52:55], v[146:149], v[190:193], v[52:55]
	v_mfma_f32_16x16x32_bf16 v[48:51], v[154:157], v[190:193], v[48:51]
	v_mfma_f32_16x16x32_bf16 v[44:47], v[146:149], v[198:201], v[44:47]
	v_mfma_f32_16x16x32_bf16 v[40:43], v[154:157], v[198:201], v[40:43]
	v_mfma_f32_16x16x32_bf16 v[36:39], v[146:149], v[206:209], v[36:39]
	v_mfma_f32_16x16x32_bf16 v[32:35], v[154:157], v[206:209], v[32:35]
	v_mfma_f32_16x16x32_bf16 v[60:63], v[150:153], v[180:183], v[60:63]
	v_mfma_f32_16x16x32_bf16 v[56:59], v[172:175], v[180:183], v[56:59]
	v_mfma_f32_16x16x32_bf16 v[52:55], v[150:153], v[194:197], v[52:55]
	v_mfma_f32_16x16x32_bf16 v[48:51], v[172:175], v[194:197], v[48:51]
	v_mfma_f32_16x16x32_bf16 v[44:47], v[150:153], v[202:205], v[44:47]
	v_mfma_f32_16x16x32_bf16 v[40:43], v[172:175], v[202:205], v[40:43]
	v_mfma_f32_16x16x32_bf16 v[36:39], v[150:153], v[210:213], v[36:39]
	v_mfma_f32_16x16x32_bf16 v[32:35], v[172:175], v[210:213], v[32:35]
	s_setprio 0
	s_barrier
; #define PG8_STAGE(bufoff, gbase, voff) do { _Pragma("unroll") for (int _i = 0; _i < 2; ++_i) \
;         __builtin_amdgcn_global_load_lds((const unsigned*)((const char*)(gbase) + (voff)[_i]), (PG8_LAS unsigned*)(lds + (bufoff) + ldsw + _i * 8192), 16, 0, 0); } while (0)
; #define PG8_LDA(dst, b, h) do { _Pragma("unroll") for (int m = 0; m < 4; ++m) _Pragma("unroll") for (int k = 0; k < 2; ++k) dst[m][k] = *(const PG8_LAS bf16x8*)(lds + PG8_SA(b, h) + aoff + m * 2048 + k * 1024); } while (0)
; #define PG8_MMA(ai, bj, At, Bt) do { __builtin_amdgcn_s_setprio(1); _Pragma("unroll") for (int m = 0; m < 4; ++m) _Pragma("unroll") for (int n = 0; n < 2; ++n) _Pragma("unroll") for (int k = 0; k < 2; ++k) \
;         acc[ai][bj][m][n] = __builtin_amdgcn_mfma_f32_16x16x32_bf16(Bt[n][k], At[m][k], acc[ai][bj][m][n], 0, 0, 0); __builtin_amdgcn_s_setprio(0); } while (0)
; #define PG8_WAIT_V(n) asm volatile("s_waitcnt vmcnt(" #n ")" ::: "memory")
; #define PG8_WAIT_L(n) asm volatile("s_waitcnt lgkmcnt(" #n ")" ::: "memory")
; #define PG8_BAR __builtin_amdgcn_s_barrier()
; #define PG8_SCHED __builtin_amdgcn_sched_barrier(0)
; template <class Epi, class Sched, bool ALIGN_EPI = false, bool SP2 = false>
; __device__ __forceinline__ void gemm_phase(PG8_LAS unsigned char* lds, const Gemm g, const Sched& S, const Epi& E, int tid_in) {
;     ...
;         for (int t = 0; t < nt; t += 2) {
;             const bool last = (t == nt - 2);
;             const char* a1 = cA + (size_t)(t + 1) * kstep;
;             const char* a2 = last ? nA : cA + (size_t)(t + 2) * kstep; const char* b2 = last ? nB : cB + (size_t)(t + 2) * kstep;
;     ...
;             PG8_LDA(At, 1, 1); PG8_STAGE(PG8_SB(1, 0), b3, voffB); PG8_STAGE(PG8_SB(1, 1), b3 + hstep, voffB); PG8_STAGE(PG8_SA(1, 0), a3, voffA);
;             PG8_WAIT_V(8); PG8_WAIT_L(0); PG8_BAR; PG8_MMA(1, 0, At, B0); PG8_MMA(1, 1, At, B1); PG8_BAR; PG8_SCHED;
	s_add_i32 s8, s43, s14
	v_lshl_add_u64 v[158:159], v[158:159], 0, s[6:7]
	s_mov_b32 m0, s8
	ds_read_b128 v[176:179], v238 offset:49152
	ds_read_b128 v[180:183], v238 offset:50176
	ds_read_b128 v[190:193], v238 offset:51200
	ds_read_b128 v[194:197], v238 offset:52224
	ds_read_b128 v[198:201], v238 offset:53248
	ds_read_b128 v[202:205], v238 offset:54272
	ds_read_b128 v[206:209], v238 offset:55296
	ds_read_b128 v[210:213], v238 offset:56320
	global_load_lds_dwordx4 v[158:159], off
	s_add_i32 m0, s8, 0x2000
	s_add_u32 s4, s4, 0x40080
	v_lshl_add_u64 v[158:159], v[184:185], 0, s[6:7]
	s_addc_u32 s5, s5, 0
	s_add_i32 s8, s44, s14
	global_load_lds_dwordx4 v[158:159], off
	v_lshl_add_u64 v[158:159], s[4:5], 0, v[162:163]
	s_mov_b32 m0, s8
	s_nop 0
	global_load_lds_dwordx4 v[158:159], off
	v_lshl_add_u64 v[158:159], s[4:5], 0, v[166:167]
	s_add_i32 m0, s8, 0x2000
	s_nop 0
	global_load_lds_dwordx4 v[158:159], off
	v_lshl_add_u64 v[158:159], v[186:187], 0, s[6:7]
	s_mov_b32 m0, s75
	s_nop 0
	global_load_lds_dwordx4 v[158:159], off
	v_lshl_add_u64 v[158:159], v[188:189], 0, s[6:7]
	s_mov_b32 m0, s76
	s_nop 0
	global_load_lds_dwordx4 v[158:159], off
	s_waitcnt vmcnt(8) lgkmcnt(0)
	s_barrier
	s_setprio 1
	v_mfma_f32_16x16x32_bf16 v[90:93], v[130:133], v[176:179], v[90:93]
	v_mfma_f32_16x16x32_bf16 v[94:97], v[138:141], v[176:179], v[94:97]
	v_mfma_f32_16x16x32_bf16 v[82:85], v[130:133], v[190:193], v[82:85]
	v_mfma_f32_16x16x32_bf16 v[86:89], v[138:141], v[190:193], v[86:89]
	v_mfma_f32_16x16x32_bf16 v[72:75], v[130:133], v[198:201], v[72:75]
	v_mfma_f32_16x16x32_bf16 v[76:79], v[138:141], v[198:201], v[76:79]
	v_mfma_f32_16x16x32_bf16 v[64:67], v[130:133], v[206:209], v[64:67]
	v_mfma_f32_16x16x32_bf16 v[68:71], v[138:141], v[206:209], v[68:71]
	v_mfma_f32_16x16x32_bf16 v[90:93], v[134:137], v[180:183], v[90:93]
	v_mfma_f32_16x16x32_bf16 v[94:97], v[142:145], v[180:183], v[94:97]
	v_mfma_f32_16x16x32_bf16 v[82:85], v[134:137], v[194:197], v[82:85]
	v_mfma_f32_16x16x32_bf16 v[86:89], v[142:145], v[194:197], v[86:89]
	v_mfma_f32_16x16x32_bf16 v[72:75], v[134:137], v[202:205], v[72:75]
	v_mfma_f32_16x16x32_bf16 v[76:79], v[142:145], v[202:205], v[76:79]
	v_mfma_f32_16x16x32_bf16 v[64:67], v[134:137], v[210:213], v[64:67]
	v_mfma_f32_16x16x32_bf16 v[68:71], v[142:145], v[210:213], v[68:71]
	v_mfma_f32_16x16x32_bf16 v[28:31], v[146:149], v[176:179], v[28:31]
	v_mfma_f32_16x16x32_bf16 v[24:27], v[154:157], v[176:179], v[24:27]
	v_mfma_f32_16x16x32_bf16 v[20:23], v[146:149], v[190:193], v[20:23]
	v_mfma_f32_16x16x32_bf16 v[16:19], v[154:157], v[190:193], v[16:19]
	v_mfma_f32_16x16x32_bf16 v[12:15], v[146:149], v[198:201], v[12:15]
	v_mfma_f32_16x16x32_bf16 v[8:11], v[154:157], v[198:201], v[8:11]
	v_mfma_f32_16x16x32_bf16 v[4:7], v[146:149], v[206:209], v[4:7]
	v_mfma_f32_16x16x32_bf16 v[0:3], v[154:157], v[206:209], v[0:3]
	v_mfma_f32_16x16x32_bf16 v[28:31], v[150:153], v[180:183], v[28:31]
	v_mfma_f32_16x16x32_bf16 v[24:27], v[172:175], v[180:183], v[24:27]
	v_mfma_f32_16x16x32_bf16 v[20:23], v[150:153], v[194:197], v[20:23]
	v_mfma_f32_16x16x32_bf16 v[16:19], v[172:175], v[194:197], v[16:19]
	v_mfma_f32_16x16x32_bf16 v[12:15], v[150:153], v[202:205], v[12:15]
	v_mfma_f32_16x16x32_bf16 v[8:11], v[172:175], v[202:205], v[8:11]
	v_mfma_f32_16x16x32_bf16 v[4:7], v[150:153], v[210:213], v[4:7]
	v_mfma_f32_16x16x32_bf16 v[0:3], v[172:175], v[210:213], v[0:3]
	s_setprio 0
	s_barrier
	s_add_i32 s42, s42, 2
	s_add_u32 s2, s2, 0x100
	s_addc_u32 s3, s3, 0
	s_add_u32 s40, s40, 0x100
	s_addc_u32 s41, s41, 0
	s_cmp_gt_u32 s42, 13
	s_cbranch_scc0 .LBB0_198
	s_and_b64 vcc, exec, s[64:65]
	s_mov_b32 s71, 0xfe03f81
	s_movk_i32 s73, 0x810
	s_cbranch_vccz .LBB0_201
	s_barrier

; #define PG8_STAGE(bufoff, gbase, voff) do { _Pragma("unroll") for (int _i = 0; _i < 2; ++_i) \
;         __builtin_amdgcn_global_load_lds((const unsigned*)((const char*)(gbase) + (voff)[_i]), (PG8_LAS unsigned*)(lds + (bufoff) + ldsw + _i * 8192), 16, 0, 0); } while (0)
; #define PG8_LDA(dst, b, h) do { _Pragma("unroll") for (int m = 0; m < 4; ++m) _Pragma("unroll") for (int k = 0; k < 2; ++k) dst[m][k] = *(const PG8_LAS bf16x8*)(lds + PG8_SA(b, h) + aoff + m * 2048 + k * 1024); } while (0)
; #define PG8_LDB(dst, b, h) do { _Pragma("unroll") for (int n = 0; n < 2; ++n) _Pragma("unroll") for (int k = 0; k < 2; ++k) dst[n][k] = *(const PG8_LAS bf16x8*)(lds + PG8_SB(b, h) + boff + n * 2048 + k * 1024); } while (0)
; #define PG8_MMA(ai, bj, At, Bt) do { __builtin_amdgcn_s_setprio(1); _Pragma("unroll") for (int m = 0; m < 4; ++m) _Pragma("unroll") for (int n = 0; n < 2; ++n) _Pragma("unroll") for (int k = 0; k < 2; ++k) \
;         acc[ai][bj][m][n] = __builtin_amdgcn_mfma_f32_16x16x32_bf16(Bt[n][k], At[m][k], acc[ai][bj][m][n], 0, 0, 0); __builtin_amdgcn_s_setprio(0); } while (0)
; #define PG8_WAIT_V(n) asm volatile("s_waitcnt vmcnt(" #n ")" ::: "memory")
; #define PG8_BAR __builtin_amdgcn_s_barrier()
; template <class Epi, class Sched, bool ALIGN_EPI = false, bool SP2 = false>
; __device__ __forceinline__ void gemm_phase(PG8_LAS unsigned char* lds, const Gemm g, const Sched& S, const Epi& E, int tid_in) {
;     ...
;         for (int t = 0; t < nt; t += 2) {
;             const bool last = (t == nt - 2);
;             const char* a1 = cA + (size_t)(t + 1) * kstep;
;             const char* a2 = last ? nA : cA + (size_t)(t + 2) * kstep; const char* b2 = last ? nB : cB + (size_t)(t + 2) * kstep;
;             const char* a3 = a2 + kstep; const char* b3 = b2 + kstep;
;             if (last && has_next) S.a_ready(nxt);
;             if constexpr (SP2) {
;             PG8_LDB(B0, 0, 0); PG8_LDB(B1, 0, 1); PG8_SCHED; PG8_LDA(At, 0, 0); PG8_STAGE(PG8_SA(1, 1), a1 + hstep, voffA);
;             PG8_WAIT_V(8); PG8_WAIT_L(0); PG8_BAR; PG8_MMA(0, 0, At, B0); PG8_MMA(0, 1, At, B1); PG8_BAR; PG8_SCHED;
;             PG8_LDA(At, 0, 1); PG8_STAGE(PG8_SB(0, 0), b2, voffB); PG8_STAGE(PG8_SB(0, 1), b2 + hstep, voffB); PG8_STAGE(PG8_SA(0, 0), a2, voffA);
;             PG8_WAIT_V(8); PG8_WAIT_L(0); PG8_BAR; PG8_MMA(1, 0, At, B0); PG8_MMA(1, 1, At, B1); PG8_BAR; PG8_SCHED;
.LBB0_1305:
	s_add_u32 s50, s48, 0xfffe0080
	s_addc_u32 s51, s49, -1
	s_add_i32 s64, 0, 0x10000
	s_cmp_eq_u32 s63, 4
	s_cselect_b32 s53, s0, s51
	s_cselect_b32 s52, s1, s50
	s_cselect_b32 s51, s39, s62
	s_cselect_b32 s50, s41, s61
	s_add_i32 s66, 0, 0x14000
	v_add_u32_e32 v142, s64, v172
	v_add_u32_e32 v168, s66, v172
	ds_read_b128 v[130:133], v142
	ds_read_b128 v[134:137], v142 offset:1024
	ds_read_b128 v[138:141], v142 offset:2048
	ds_read_b128 v[142:145], v142 offset:3072
	ds_read_b128 v[146:149], v168
	ds_read_b128 v[160:163], v168 offset:1024
	ds_read_b128 v[164:167], v168 offset:2048
	ds_read_b128 v[174:177], v168 offset:3072
	v_lshl_add_u64 v[168:169], s[48:49], 0, v[156:157]
	s_add_i32 m0, s16, 0xc000
	ds_read_b128 v[178:181], v173
	ds_read_b128 v[182:185], v173 offset:1024
	ds_read_b128 v[190:193], v173 offset:2048
	ds_read_b128 v[194:197], v173 offset:3072
	ds_read_b128 v[198:201], v173 offset:4096
	ds_read_b128 v[202:205], v173 offset:5120
	ds_read_b128 v[206:209], v173 offset:6144
	ds_read_b128 v[210:213], v173 offset:7168
	global_load_lds_dwordx4 v[168:169], off
	v_lshl_add_u64 v[168:169], s[48:49], 0, v[158:159]
	s_add_i32 m0, s16, 0xe000
	s_nop 0
	global_load_lds_dwordx4 v[168:169], off
	s_waitcnt vmcnt(8) lgkmcnt(0)
	s_barrier
	s_setprio 1
	v_mfma_f32_16x16x32_bf16 v[126:129], v[130:133], v[178:181], v[126:129]
	v_mfma_f32_16x16x32_bf16 v[122:125], v[138:141], v[178:181], v[122:125]
	v_mfma_f32_16x16x32_bf16 v[110:113], v[130:133], v[190:193], v[110:113]
	v_mfma_f32_16x16x32_bf16 v[106:109], v[138:141], v[190:193], v[106:109]
	v_mfma_f32_16x16x32_bf16 v[98:101], v[130:133], v[198:201], v[98:101]
	v_mfma_f32_16x16x32_bf16 v[90:93], v[138:141], v[198:201], v[90:93]
	v_mfma_f32_16x16x32_bf16 v[82:85], v[130:133], v[206:209], v[82:85]
	v_mfma_f32_16x16x32_bf16 v[72:75], v[138:141], v[206:209], v[72:75]
	v_mfma_f32_16x16x32_bf16 v[126:129], v[134:137], v[182:185], v[126:129]
	v_mfma_f32_16x16x32_bf16 v[122:125], v[142:145], v[182:185], v[122:125]
	v_mfma_f32_16x16x32_bf16 v[110:113], v[134:137], v[194:197], v[110:113]
	v_mfma_f32_16x16x32_bf16 v[106:109], v[142:145], v[194:197], v[106:109]
	v_mfma_f32_16x16x32_bf16 v[98:101], v[134:137], v[202:205], v[98:101]
	v_mfma_f32_16x16x32_bf16 v[90:93], v[142:145], v[202:205], v[90:93]
	v_mfma_f32_16x16x32_bf16 v[82:85], v[134:137], v[210:213], v[82:85]
	v_mfma_f32_16x16x32_bf16 v[72:75], v[142:145], v[210:213], v[72:75]
	v_mfma_f32_16x16x32_bf16 v[118:121], v[146:149], v[178:181], v[118:121]
	v_mfma_f32_16x16x32_bf16 v[114:117], v[164:167], v[178:181], v[114:117]
	v_mfma_f32_16x16x32_bf16 v[102:105], v[146:149], v[190:193], v[102:105]
	v_mfma_f32_16x16x32_bf16 v[94:97], v[164:167], v[190:193], v[94:97]
	v_mfma_f32_16x16x32_bf16 v[86:89], v[146:149], v[198:201], v[86:89]
	v_mfma_f32_16x16x32_bf16 v[76:79], v[164:167], v[198:201], v[76:79]
	v_mfma_f32_16x16x32_bf16 v[68:71], v[146:149], v[206:209], v[68:71]
	v_mfma_f32_16x16x32_bf16 v[64:67], v[164:167], v[206:209], v[64:67]
	v_mfma_f32_16x16x32_bf16 v[118:121], v[160:163], v[182:185], v[118:121]
	v_mfma_f32_16x16x32_bf16 v[114:117], v[174:177], v[182:185], v[114:117]
	v_mfma_f32_16x16x32_bf16 v[102:105], v[160:163], v[194:197], v[102:105]
	v_mfma_f32_16x16x32_bf16 v[94:97], v[174:177], v[194:197], v[94:97]
	v_mfma_f32_16x16x32_bf16 v[86:89], v[160:163], v[202:205], v[86:89]
	v_mfma_f32_16x16x32_bf16 v[76:79], v[174:177], v[202:205], v[76:79]
	v_mfma_f32_16x16x32_bf16 v[68:71], v[160:163], v[210:213], v[68:71]
	v_mfma_f32_16x16x32_bf16 v[64:67], v[174:177], v[210:213], v[64:67]
	s_setprio 0
	s_barrier
	s_add_i32 s64, s64, s15
	v_lshl_add_u64 v[168:169], s[50:51], 0, v[80:81]
	s_mov_b32 m0, s64
	ds_read_b128 v[178:181], v173 offset:16384
	ds_read_b128 v[182:185], v173 offset:17408
	ds_read_b128 v[190:193], v173 offset:18432
	ds_read_b128 v[194:197], v173 offset:19456
	ds_read_b128 v[198:201], v173 offset:20480
	ds_read_b128 v[202:205], v173 offset:21504
	ds_read_b128 v[206:209], v173 offset:22528
	ds_read_b128 v[210:213], v173 offset:23552
	global_load_lds_dwordx4 v[168:169], off
	s_add_i32 m0, s64, 0x2000
	s_add_u32 s64, s50, 0x20000
	v_lshl_add_u64 v[186:187], s[50:51], 0, v[154:155]
	s_addc_u32 s65, s51, 0
	s_add_i32 s66, s66, s15
	global_load_lds_dwordx4 v[186:187], off
	v_lshl_add_u64 v[188:189], s[64:65], 0, v[80:81]
	s_mov_b32 m0, s66
	v_lshl_add_u64 v[214:215], s[52:53], 0, v[152:153]
	global_load_lds_dwordx4 v[188:189], off
	v_lshl_add_u64 v[188:189], s[64:65], 0, v[154:155]
	s_add_i32 m0, s66, 0x2000
	s_nop 0
	global_load_lds_dwordx4 v[188:189], off
	v_lshl_add_u64 v[188:189], s[52:53], 0, v[150:151]
	s_mov_b32 m0, s16
	s_nop 0
	global_load_lds_dwordx4 v[188:189], off
	s_mov_b32 m0, s17
	s_nop 0
	global_load_lds_dwordx4 v[214:215], off
	s_waitcnt vmcnt(8) lgkmcnt(0)
	s_barrier
; #define PG8_STAGE(bufoff, gbase, voff) do { _Pragma("unroll") for (int _i = 0; _i < 2; ++_i) \
;         __builtin_amdgcn_global_load_lds((const unsigned*)((const char*)(gbase) + (voff)[_i]), (PG8_LAS unsigned*)(lds + (bufoff) + ldsw + _i * 8192), 16, 0, 0); } while (0)
; #define PG8_LDA(dst, b, h) do { _Pragma("unroll") for (int m = 0; m < 4; ++m) _Pragma("unroll") for (int k = 0; k < 2; ++k) dst[m][k] = *(const PG8_LAS bf16x8*)(lds + PG8_SA(b, h) + aoff + m * 2048 + k * 1024); } while (0)
; #define PG8_LDB(dst, b, h) do { _Pragma("unroll") for (int n = 0; n < 2; ++n) _Pragma("unroll") for (int k = 0; k < 2; ++k) dst[n][k] = *(const PG8_LAS bf16x8*)(lds + PG8_SB(b, h) + boff + n * 2048 + k * 1024); } while (0)
; #define PG8_MMA(ai, bj, At, Bt) do { __builtin_amdgcn_s_setprio(1); _Pragma("unroll") for (int m = 0; m < 4; ++m) _Pragma("unroll") for (int n = 0; n < 2; ++n) _Pragma("unroll") for (int k = 0; k < 2; ++k) \
;         acc[ai][bj][m][n] = __builtin_amdgcn_mfma_f32_16x16x32_bf16(Bt[n][k], At[m][k], acc[ai][bj][m][n], 0, 0, 0); __builtin_amdgcn_s_setprio(0); } while (0)
; #define PG8_WAIT_V(n) asm volatile("s_waitcnt vmcnt(" #n ")" ::: "memory")
; #define PG8_WAIT_L(n) asm volatile("s_waitcnt lgkmcnt(" #n ")" ::: "memory")
; #define PG8_BAR __builtin_amdgcn_s_barrier()
; #define PG8_SCHED __builtin_amdgcn_sched_barrier(0)
; template <class Epi, class Sched, bool ALIGN_EPI = false, bool SP2 = false>
; __device__ __forceinline__ void gemm_phase(PG8_LAS unsigned char* lds, const Gemm g, const Sched& S, const Epi& E, int tid_in) {
;     ...
;             PG8_WAIT_V(8); PG8_WAIT_L(0); PG8_BAR; PG8_MMA(1, 0, At, B0); PG8_MMA(1, 1, At, B1); PG8_BAR; PG8_SCHED;
;             PG8_LDB(B0, 1, 0); PG8_LDB(B1, 1, 1); PG8_SCHED; PG8_LDA(At, 1, 0); PG8_STAGE(PG8_SA(0, 1), a2 + hstep, voffA);
;             PG8_WAIT_V(8); PG8_WAIT_L(0); PG8_BAR; PG8_MMA(0, 0, At, B0); PG8_MMA(0, 1, At, B1); PG8_BAR; PG8_SCHED;
	s_setprio 1
	v_mfma_f32_16x16x32_bf16 v[60:63], v[130:133], v[178:181], v[60:63]
	v_mfma_f32_16x16x32_bf16 v[56:59], v[138:141], v[178:181], v[56:59]
	v_mfma_f32_16x16x32_bf16 v[48:51], v[130:133], v[190:193], v[48:51]
	v_mfma_f32_16x16x32_bf16 v[40:43], v[138:141], v[190:193], v[40:43]
	v_mfma_f32_16x16x32_bf16 v[32:35], v[130:133], v[198:201], v[32:35]
	v_mfma_f32_16x16x32_bf16 v[24:27], v[138:141], v[198:201], v[24:27]
	v_mfma_f32_16x16x32_bf16 v[16:19], v[130:133], v[206:209], v[16:19]
	v_mfma_f32_16x16x32_bf16 v[8:11], v[138:141], v[206:209], v[8:11]
	v_mfma_f32_16x16x32_bf16 v[60:63], v[134:137], v[182:185], v[60:63]
	v_mfma_f32_16x16x32_bf16 v[56:59], v[142:145], v[182:185], v[56:59]
	v_mfma_f32_16x16x32_bf16 v[48:51], v[134:137], v[194:197], v[48:51]
	v_mfma_f32_16x16x32_bf16 v[40:43], v[142:145], v[194:197], v[40:43]
	v_mfma_f32_16x16x32_bf16 v[32:35], v[134:137], v[202:205], v[32:35]
	v_mfma_f32_16x16x32_bf16 v[24:27], v[142:145], v[202:205], v[24:27]
	v_mfma_f32_16x16x32_bf16 v[16:19], v[134:137], v[210:213], v[16:19]
	v_mfma_f32_16x16x32_bf16 v[8:11], v[142:145], v[210:213], v[8:11]
	v_mfma_f32_16x16x32_bf16 v[52:55], v[146:149], v[178:181], v[52:55]
	v_mfma_f32_16x16x32_bf16 v[44:47], v[164:167], v[178:181], v[44:47]
	v_mfma_f32_16x16x32_bf16 v[36:39], v[146:149], v[190:193], v[36:39]
	v_mfma_f32_16x16x32_bf16 v[28:31], v[164:167], v[190:193], v[28:31]
	v_mfma_f32_16x16x32_bf16 v[20:23], v[146:149], v[198:201], v[20:23]
	v_mfma_f32_16x16x32_bf16 v[12:15], v[164:167], v[198:201], v[12:15]
	v_mfma_f32_16x16x32_bf16 v[4:7], v[146:149], v[206:209], v[4:7]
	v_mfma_f32_16x16x32_bf16 v[0:3], v[164:167], v[206:209], v[0:3]
	v_mfma_f32_16x16x32_bf16 v[52:55], v[160:163], v[182:185], v[52:55]
	v_mfma_f32_16x16x32_bf16 v[44:47], v[174:177], v[182:185], v[44:47]
	v_mfma_f32_16x16x32_bf16 v[36:39], v[160:163], v[194:197], v[36:39]
	v_mfma_f32_16x16x32_bf16 v[28:31], v[174:177], v[194:197], v[28:31]
	v_mfma_f32_16x16x32_bf16 v[20:23], v[160:163], v[202:205], v[20:23]
	v_mfma_f32_16x16x32_bf16 v[12:15], v[174:177], v[202:205], v[12:15]
	v_mfma_f32_16x16x32_bf16 v[4:7], v[160:163], v[210:213], v[4:7]
	v_mfma_f32_16x16x32_bf16 v[0:3], v[174:177], v[210:213], v[0:3]
	s_setprio 0
	s_barrier
	s_add_i32 s64, 0, 0x18000
	s_add_i32 s65, 0, 0x1c000
	v_add_u32_e32 v142, s64, v172
	v_add_u32_e32 v174, s65, v172
	ds_read_b128 v[130:133], v142
	ds_read_b128 v[134:137], v142 offset:1024
	ds_read_b128 v[138:141], v142 offset:2048
	ds_read_b128 v[142:145], v142 offset:3072
	ds_read_b128 v[146:149], v174
	ds_read_b128 v[160:163], v174 offset:1024
	ds_read_b128 v[164:167], v174 offset:2048
	ds_read_b128 v[174:177], v174 offset:3072
	s_add_u32 s52, s52, 0x20000
	s_addc_u32 s53, s53, 0
	s_mov_b32 m0, s18
	v_lshl_add_u64 v[226:227], s[52:53], 0, v[150:151]
	ds_read_b128 v[178:181], v173 offset:32768
	ds_read_b128 v[182:185], v173 offset:33792
	ds_read_b128 v[190:193], v173 offset:34816
	ds_read_b128 v[194:197], v173 offset:35840
	ds_read_b128 v[198:201], v173 offset:36864
	ds_read_b128 v[202:205], v173 offset:37888
	ds_read_b128 v[206:209], v173 offset:38912
	ds_read_b128 v[210:213], v173 offset:39936
	global_load_lds_dwordx4 v[226:227], off
	v_lshl_add_u64 v[226:227], s[52:53], 0, v[152:153]
	s_mov_b32 m0, s19
	s_nop 0
	global_load_lds_dwordx4 v[226:227], off
	s_waitcnt vmcnt(8) lgkmcnt(0)
	s_barrier
	s_setprio 1
	v_mfma_f32_16x16x32_bf16 v[126:129], v[130:133], v[178:181], v[126:129]
	v_mfma_f32_16x16x32_bf16 v[122:125], v[138:141], v[178:181], v[122:125]
	v_mfma_f32_16x16x32_bf16 v[110:113], v[130:133], v[190:193], v[110:113]
	v_mfma_f32_16x16x32_bf16 v[106:109], v[138:141], v[190:193], v[106:109]
	v_mfma_f32_16x16x32_bf16 v[98:101], v[130:133], v[198:201], v[98:101]
	v_mfma_f32_16x16x32_bf16 v[90:93], v[138:141], v[198:201], v[90:93]
	v_mfma_f32_16x16x32_bf16 v[82:85], v[130:133], v[206:209], v[82:85]
	v_mfma_f32_16x16x32_bf16 v[72:75], v[138:141], v[206:209], v[72:75]
	v_mfma_f32_16x16x32_bf16 v[126:129], v[134:137], v[182:185], v[126:129]
	v_mfma_f32_16x16x32_bf16 v[122:125], v[142:145], v[182:185], v[122:125]
	v_mfma_f32_16x16x32_bf16 v[110:113], v[134:137], v[194:197], v[110:113]
	v_mfma_f32_16x16x32_bf16 v[106:109], v[142:145], v[194:197], v[106:109]
	v_mfma_f32_16x16x32_bf16 v[98:101], v[134:137], v[202:205], v[98:101]
	v_mfma_f32_16x16x32_bf16 v[90:93], v[142:145], v[202:205], v[90:93]
	v_mfma_f32_16x16x32_bf16 v[82:85], v[134:137], v[210:213], v[82:85]
	v_mfma_f32_16x16x32_bf16 v[72:75], v[142:145], v[210:213], v[72:75]
	v_mfma_f32_16x16x32_bf16 v[118:121], v[146:149], v[178:181], v[118:121]
	v_mfma_f32_16x16x32_bf16 v[114:117], v[164:167], v[178:181], v[114:117]
	v_mfma_f32_16x16x32_bf16 v[102:105], v[146:149], v[190:193], v[102:105]
	v_mfma_f32_16x16x32_bf16 v[94:97], v[164:167], v[190:193], v[94:97]
	v_mfma_f32_16x16x32_bf16 v[86:89], v[146:149], v[198:201], v[86:89]
	v_mfma_f32_16x16x32_bf16 v[76:79], v[164:167], v[198:201], v[76:79]
	v_mfma_f32_16x16x32_bf16 v[68:71], v[146:149], v[206:209], v[68:71]
	v_mfma_f32_16x16x32_bf16 v[64:67], v[164:167], v[206:209], v[64:67]
	v_mfma_f32_16x16x32_bf16 v[118:121], v[160:163], v[182:185], v[118:121]
	v_mfma_f32_16x16x32_bf16 v[114:117], v[174:177], v[182:185], v[114:117]
	v_mfma_f32_16x16x32_bf16 v[102:105], v[160:163], v[194:197], v[102:105]
	v_mfma_f32_16x16x32_bf16 v[94:97], v[174:177], v[194:197], v[94:97]
	v_mfma_f32_16x16x32_bf16 v[86:89], v[160:163], v[202:205], v[86:89]
	v_mfma_f32_16x16x32_bf16 v[76:79], v[174:177], v[202:205], v[76:79]
	v_mfma_f32_16x16x32_bf16 v[68:71], v[160:163], v[210:213], v[68:71]
	v_mfma_f32_16x16x32_bf16 v[64:67], v[174:177], v[210:213], v[64:67]
	s_setprio 0
	s_barrier
; #define PG8_STAGE(bufoff, gbase, voff) do { _Pragma("unroll") for (int _i = 0; _i < 2; ++_i) \
;         __builtin_amdgcn_global_load_lds((const unsigned*)((const char*)(gbase) + (voff)[_i]), (PG8_LAS unsigned*)(lds + (bufoff) + ldsw + _i * 8192), 16, 0, 0); } while (0)
; #define PG8_LDA(dst, b, h) do { _Pragma("unroll") for (int m = 0; m < 4; ++m) _Pragma("unroll") for (int k = 0; k < 2; ++k) dst[m][k] = *(const PG8_LAS bf16x8*)(lds + PG8_SA(b, h) + aoff + m * 2048 + k * 1024); } while (0)
; #define PG8_MMA(ai, bj, At, Bt) do { __builtin_amdgcn_s_setprio(1); _Pragma("unroll") for (int m = 0; m < 4; ++m) _Pragma("unroll") for (int n = 0; n < 2; ++n) _Pragma("unroll") for (int k = 0; k < 2; ++k) \
;         acc[ai][bj][m][n] = __builtin_amdgcn_mfma_f32_16x16x32_bf16(Bt[n][k], At[m][k], acc[ai][bj][m][n], 0, 0, 0); __builtin_amdgcn_s_setprio(0); } while (0)
; #define PG8_WAIT_V(n) asm volatile("s_waitcnt vmcnt(" #n ")" ::: "memory")
; #define PG8_WAIT_L(n) asm volatile("s_waitcnt lgkmcnt(" #n ")" ::: "memory")
; #define PG8_BAR __builtin_amdgcn_s_barrier()
; #define PG8_SCHED __builtin_amdgcn_sched_barrier(0)
; template <class Epi, class Sched, bool ALIGN_EPI = false, bool SP2 = false>
; __device__ __forceinline__ void gemm_phase(PG8_LAS unsigned char* lds, const Gemm g, const Sched& S, const Epi& E, int tid_in) {
;     ...
;         for (int t = 0; t < nt; t += 2) {
;             const bool last = (t == nt - 2);
;             const char* a1 = cA + (size_t)(t + 1) * kstep;
;             const char* a2 = last ? nA : cA + (size_t)(t + 2) * kstep; const char* b2 = last ? nB : cB + (size_t)(t + 2) * kstep;
;     ...
;             PG8_LDA(At, 1, 1); PG8_STAGE(PG8_SB(1, 0), b3, voffB); PG8_STAGE(PG8_SB(1, 1), b3 + hstep, voffB); PG8_STAGE(PG8_SA(1, 0), a3, voffA);
;             PG8_WAIT_V(8); PG8_WAIT_L(0); PG8_BAR; PG8_MMA(1, 0, At, B0); PG8_MMA(1, 1, At, B1); PG8_BAR; PG8_SCHED;
	s_add_i32 s52, s64, s15
	v_lshl_add_u64 v[168:169], v[168:169], 0, s[6:7]
	s_mov_b32 m0, s52
	ds_read_b128 v[178:181], v173 offset:49152
	ds_read_b128 v[182:185], v173 offset:50176
	ds_read_b128 v[190:193], v173 offset:51200
	ds_read_b128 v[194:197], v173 offset:52224
	ds_read_b128 v[198:201], v173 offset:53248
	ds_read_b128 v[202:205], v173 offset:54272
	ds_read_b128 v[206:209], v173 offset:55296
	ds_read_b128 v[210:213], v173 offset:56320
	global_load_lds_dwordx4 v[168:169], off
	s_add_i32 m0, s52, 0x2000
	s_add_u32 s50, s50, 0x20080
	v_lshl_add_u64 v[168:169], v[186:187], 0, s[6:7]
	s_addc_u32 s51, s51, 0
	s_add_i32 s52, s65, s15
	global_load_lds_dwordx4 v[168:169], off
	v_lshl_add_u64 v[168:169], s[50:51], 0, v[80:81]
	s_mov_b32 m0, s52
	s_nop 0
	global_load_lds_dwordx4 v[168:169], off
	v_lshl_add_u64 v[168:169], s[50:51], 0, v[154:155]
	s_add_i32 m0, s52, 0x2000
	s_nop 0
	global_load_lds_dwordx4 v[168:169], off
	v_lshl_add_u64 v[168:169], v[188:189], 0, s[6:7]
	s_mov_b32 m0, s54
	s_nop 0
	global_load_lds_dwordx4 v[168:169], off
	v_lshl_add_u64 v[168:169], v[214:215], 0, s[6:7]
	s_mov_b32 m0, s55
	s_nop 0
	global_load_lds_dwordx4 v[168:169], off
	s_waitcnt vmcnt(8) lgkmcnt(0)
	s_barrier
	s_setprio 1
	v_mfma_f32_16x16x32_bf16 v[60:63], v[130:133], v[178:181], v[60:63]
	v_mfma_f32_16x16x32_bf16 v[56:59], v[138:141], v[178:181], v[56:59]
	v_mfma_f32_16x16x32_bf16 v[48:51], v[130:133], v[190:193], v[48:51]
	v_mfma_f32_16x16x32_bf16 v[40:43], v[138:141], v[190:193], v[40:43]
	v_mfma_f32_16x16x32_bf16 v[32:35], v[130:133], v[198:201], v[32:35]
	v_mfma_f32_16x16x32_bf16 v[24:27], v[138:141], v[198:201], v[24:27]
	v_mfma_f32_16x16x32_bf16 v[16:19], v[130:133], v[206:209], v[16:19]
	v_mfma_f32_16x16x32_bf16 v[8:11], v[138:141], v[206:209], v[8:11]
	v_mfma_f32_16x16x32_bf16 v[60:63], v[134:137], v[182:185], v[60:63]
	v_mfma_f32_16x16x32_bf16 v[56:59], v[142:145], v[182:185], v[56:59]
	v_mfma_f32_16x16x32_bf16 v[48:51], v[134:137], v[194:197], v[48:51]
	v_mfma_f32_16x16x32_bf16 v[40:43], v[142:145], v[194:197], v[40:43]
	v_mfma_f32_16x16x32_bf16 v[32:35], v[134:137], v[202:205], v[32:35]
	v_mfma_f32_16x16x32_bf16 v[24:27], v[142:145], v[202:205], v[24:27]
	v_mfma_f32_16x16x32_bf16 v[16:19], v[134:137], v[210:213], v[16:19]
	v_mfma_f32_16x16x32_bf16 v[8:11], v[142:145], v[210:213], v[8:11]
	v_mfma_f32_16x16x32_bf16 v[52:55], v[146:149], v[178:181], v[52:55]
	v_mfma_f32_16x16x32_bf16 v[44:47], v[164:167], v[178:181], v[44:47]
	v_mfma_f32_16x16x32_bf16 v[36:39], v[146:149], v[190:193], v[36:39]
	v_mfma_f32_16x16x32_bf16 v[28:31], v[164:167], v[190:193], v[28:31]
	v_mfma_f32_16x16x32_bf16 v[20:23], v[146:149], v[198:201], v[20:23]
	v_mfma_f32_16x16x32_bf16 v[12:15], v[164:167], v[198:201], v[12:15]
	v_mfma_f32_16x16x32_bf16 v[4:7], v[146:149], v[206:209], v[4:7]
	v_mfma_f32_16x16x32_bf16 v[0:3], v[164:167], v[206:209], v[0:3]
	v_mfma_f32_16x16x32_bf16 v[52:55], v[160:163], v[182:185], v[52:55]
	v_mfma_f32_16x16x32_bf16 v[44:47], v[174:177], v[182:185], v[44:47]
	v_mfma_f32_16x16x32_bf16 v[36:39], v[160:163], v[194:197], v[36:39]
	v_mfma_f32_16x16x32_bf16 v[28:31], v[174:177], v[194:197], v[28:31]
	v_mfma_f32_16x16x32_bf16 v[20:23], v[160:163], v[202:205], v[20:23]
	v_mfma_f32_16x16x32_bf16 v[12:15], v[174:177], v[202:205], v[12:15]
	v_mfma_f32_16x16x32_bf16 v[4:7], v[160:163], v[210:213], v[4:7]
	v_mfma_f32_16x16x32_bf16 v[0:3], v[174:177], v[210:213], v[0:3]
	s_setprio 0
	s_barrier
	s_add_i32 s63, s63, 2
	s_add_u32 s48, s48, 0x100
	s_addc_u32 s49, s49, 0
	s_add_u32 s61, s61, 0x100
	s_addc_u32 s62, s62, 0
	s_cmp_gt_u32 s63, 5
	s_cbranch_scc0 .LBB0_1305
	s_and_b64 vcc, exec, s[8:9]
	s_cbranch_vccz .LBB0_1308
	s_barrier

; #define PG8_STAGE(bufoff, gbase, voff) do { _Pragma("unroll") for (int _i = 0; _i < 2; ++_i) \
;         __builtin_amdgcn_global_load_lds((const unsigned*)((const char*)(gbase) + (voff)[_i]), (PG8_LAS unsigned*)(lds + (bufoff) + ldsw + _i * 8192), 16, 0, 0); } while (0)
; #define PG8_LDA(dst, b, h) do { _Pragma("unroll") for (int m = 0; m < 4; ++m) _Pragma("unroll") for (int k = 0; k < 2; ++k) dst[m][k] = *(const PG8_LAS bf16x8*)(lds + PG8_SA(b, h) + aoff + m * 2048 + k * 1024); } while (0)
; #define PG8_LDB(dst, b, h) do { _Pragma("unroll") for (int n = 0; n < 2; ++n) _Pragma("unroll") for (int k = 0; k < 2; ++k) dst[n][k] = *(const PG8_LAS bf16x8*)(lds + PG8_SB(b, h) + boff + n * 2048 + k * 1024); } while (0)
; #define PG8_MMA(ai, bj, At, Bt) do { __builtin_amdgcn_s_setprio(1); _Pragma("unroll") for (int m = 0; m < 4; ++m) _Pragma("unroll") for (int n = 0; n < 2; ++n) _Pragma("unroll") for (int k = 0; k < 2; ++k) \
;         acc[ai][bj][m][n] = __builtin_amdgcn_mfma_f32_16x16x32_bf16(Bt[n][k], At[m][k], acc[ai][bj][m][n], 0, 0, 0); __builtin_amdgcn_s_setprio(0); } while (0)
; #define PG8_WAIT_V(n) asm volatile("s_waitcnt vmcnt(" #n ")" ::: "memory")
; #define PG8_BAR __builtin_amdgcn_s_barrier()
; template <class Epi, class Sched, bool ALIGN_EPI = false, bool SP2 = false>
; __device__ __forceinline__ void gemm_phase(PG8_LAS unsigned char* lds, const Gemm g, const Sched& S, const Epi& E, int tid_in) {
;     ...
;         for (int t = 0; t < nt; t += 2) {
;             const bool last = (t == nt - 2);
;             const char* a1 = cA + (size_t)(t + 1) * kstep;
;             const char* a2 = last ? nA : cA + (size_t)(t + 2) * kstep; const char* b2 = last ? nB : cB + (size_t)(t + 2) * kstep;
;             const char* a3 = a2 + kstep; const char* b3 = b2 + kstep;
;             if (last && has_next) S.a_ready(nxt);
;             if constexpr (SP2) {
;             PG8_LDB(B0, 0, 0); PG8_LDB(B1, 0, 1); PG8_SCHED; PG8_LDA(At, 0, 0); PG8_STAGE(PG8_SA(1, 1), a1 + hstep, voffA);
;             PG8_WAIT_V(8); PG8_WAIT_L(0); PG8_BAR; PG8_MMA(0, 0, At, B0); PG8_MMA(0, 1, At, B1); PG8_BAR; PG8_SCHED;
;             PG8_LDA(At, 0, 1); PG8_STAGE(PG8_SB(0, 0), b2, voffB); PG8_STAGE(PG8_SB(0, 1), b2 + hstep, voffB); PG8_STAGE(PG8_SA(0, 0), a2, voffA);
;             PG8_WAIT_V(8); PG8_WAIT_L(0); PG8_BAR; PG8_MMA(1, 0, At, B0); PG8_MMA(1, 1, At, B1); PG8_BAR; PG8_SCHED;
.LBB0_1340:
	s_add_u32 s54, s52, 0xfffc0080
	s_addc_u32 s55, s53, -1
	s_add_i32 s66, 0, 0x10000
	s_cmp_eq_u32 s65, 12
	s_cselect_b32 s57, s0, s55
	s_cselect_b32 s56, s1, s54
	s_cselect_b32 s55, s41, s64
	s_cselect_b32 s54, s45, s63
	s_add_i32 s68, 0, 0x14000
	v_add_u32_e32 v142, s66, v214
	v_add_u32_e32 v158, s68, v214
	ds_read_b128 v[130:133], v142
	ds_read_b128 v[134:137], v142 offset:1024
	ds_read_b128 v[138:141], v142 offset:2048
	ds_read_b128 v[142:145], v142 offset:3072
	ds_read_b128 v[146:149], v158
	ds_read_b128 v[150:153], v158 offset:1024
	ds_read_b128 v[154:157], v158 offset:2048
	ds_read_b128 v[158:161], v158 offset:3072
	v_lshl_add_u64 v[186:187], s[52:53], 0, v[196:197]
	s_add_i32 m0, s16, 0xc000
	ds_read_b128 v[162:165], v215
	ds_read_b128 v[166:169], v215 offset:1024
	ds_read_b128 v[170:173], v215 offset:2048
	ds_read_b128 v[174:177], v215 offset:3072
	ds_read_b128 v[178:181], v215 offset:4096
	ds_read_b128 v[182:185], v215 offset:5120
	ds_read_b128 v[200:203], v215 offset:6144
	ds_read_b128 v[204:207], v215 offset:7168
	global_load_lds_dwordx4 v[186:187], off
	v_lshl_add_u64 v[186:187], s[52:53], 0, v[198:199]
	s_add_i32 m0, s16, 0xe000
	s_nop 0
	global_load_lds_dwordx4 v[186:187], off
	s_waitcnt vmcnt(8) lgkmcnt(0)
	s_barrier
	s_setprio 1
	v_mfma_f32_16x16x32_bf16 v[126:129], v[130:133], v[162:165], v[126:129]
	v_mfma_f32_16x16x32_bf16 v[122:125], v[138:141], v[162:165], v[122:125]
	v_mfma_f32_16x16x32_bf16 v[110:113], v[130:133], v[170:173], v[110:113]
	v_mfma_f32_16x16x32_bf16 v[106:109], v[138:141], v[170:173], v[106:109]
	v_mfma_f32_16x16x32_bf16 v[94:97], v[130:133], v[178:181], v[94:97]
	v_mfma_f32_16x16x32_bf16 v[90:93], v[138:141], v[178:181], v[90:93]
	v_mfma_f32_16x16x32_bf16 v[76:79], v[130:133], v[200:203], v[76:79]
	v_mfma_f32_16x16x32_bf16 v[72:75], v[138:141], v[200:203], v[72:75]
	v_mfma_f32_16x16x32_bf16 v[126:129], v[134:137], v[166:169], v[126:129]
	v_mfma_f32_16x16x32_bf16 v[122:125], v[142:145], v[166:169], v[122:125]
	v_mfma_f32_16x16x32_bf16 v[110:113], v[134:137], v[174:177], v[110:113]
	v_mfma_f32_16x16x32_bf16 v[106:109], v[142:145], v[174:177], v[106:109]
	v_mfma_f32_16x16x32_bf16 v[94:97], v[134:137], v[182:185], v[94:97]
	v_mfma_f32_16x16x32_bf16 v[90:93], v[142:145], v[182:185], v[90:93]
	v_mfma_f32_16x16x32_bf16 v[76:79], v[134:137], v[204:207], v[76:79]
	v_mfma_f32_16x16x32_bf16 v[72:75], v[142:145], v[204:207], v[72:75]
	v_mfma_f32_16x16x32_bf16 v[118:121], v[146:149], v[162:165], v[118:121]
	v_mfma_f32_16x16x32_bf16 v[114:117], v[154:157], v[162:165], v[114:117]
	v_mfma_f32_16x16x32_bf16 v[102:105], v[146:149], v[170:173], v[102:105]
	v_mfma_f32_16x16x32_bf16 v[98:101], v[154:157], v[170:173], v[98:101]
	v_mfma_f32_16x16x32_bf16 v[86:89], v[146:149], v[178:181], v[86:89]
	v_mfma_f32_16x16x32_bf16 v[82:85], v[154:157], v[178:181], v[82:85]
	v_mfma_f32_16x16x32_bf16 v[68:71], v[146:149], v[200:203], v[68:71]
	v_mfma_f32_16x16x32_bf16 v[64:67], v[154:157], v[200:203], v[64:67]
	v_mfma_f32_16x16x32_bf16 v[118:121], v[150:153], v[166:169], v[118:121]
	v_mfma_f32_16x16x32_bf16 v[114:117], v[158:161], v[166:169], v[114:117]
	v_mfma_f32_16x16x32_bf16 v[102:105], v[150:153], v[174:177], v[102:105]
	v_mfma_f32_16x16x32_bf16 v[98:101], v[158:161], v[174:177], v[98:101]
	v_mfma_f32_16x16x32_bf16 v[86:89], v[150:153], v[182:185], v[86:89]
	v_mfma_f32_16x16x32_bf16 v[82:85], v[158:161], v[182:185], v[82:85]
	v_mfma_f32_16x16x32_bf16 v[68:71], v[150:153], v[204:207], v[68:71]
	v_mfma_f32_16x16x32_bf16 v[64:67], v[158:161], v[204:207], v[64:67]
	s_setprio 0
	s_barrier
	s_add_i32 s66, s66, s15
	v_lshl_add_u64 v[186:187], s[54:55], 0, v[80:81]
	s_mov_b32 m0, s66
	ds_read_b128 v[162:165], v215 offset:16384
	ds_read_b128 v[166:169], v215 offset:17408
	ds_read_b128 v[170:173], v215 offset:18432
	ds_read_b128 v[174:177], v215 offset:19456
	ds_read_b128 v[178:181], v215 offset:20480
	ds_read_b128 v[182:185], v215 offset:21504
	ds_read_b128 v[200:203], v215 offset:22528
	ds_read_b128 v[204:207], v215 offset:23552
	global_load_lds_dwordx4 v[186:187], off
	s_add_i32 m0, s66, 0x2000
	s_add_u32 s66, s54, 0x40000
	v_lshl_add_u64 v[188:189], s[54:55], 0, v[194:195]
	s_addc_u32 s67, s55, 0
	s_add_i32 s68, s68, s15
	global_load_lds_dwordx4 v[188:189], off
	v_lshl_add_u64 v[208:209], s[66:67], 0, v[80:81]
	s_mov_b32 m0, s68
	v_lshl_add_u64 v[210:211], s[56:57], 0, v[192:193]
	global_load_lds_dwordx4 v[208:209], off
	v_lshl_add_u64 v[208:209], s[66:67], 0, v[194:195]
	s_add_i32 m0, s68, 0x2000
	s_nop 0
	global_load_lds_dwordx4 v[208:209], off
	v_lshl_add_u64 v[208:209], s[56:57], 0, v[190:191]
	s_mov_b32 m0, s16
	s_nop 0
	global_load_lds_dwordx4 v[208:209], off
	s_mov_b32 m0, s17
	s_nop 0
	global_load_lds_dwordx4 v[210:211], off
	s_waitcnt vmcnt(8) lgkmcnt(0)
	s_barrier
; #define PG8_STAGE(bufoff, gbase, voff) do { _Pragma("unroll") for (int _i = 0; _i < 2; ++_i) \
;         __builtin_amdgcn_global_load_lds((const unsigned*)((const char*)(gbase) + (voff)[_i]), (PG8_LAS unsigned*)(lds + (bufoff) + ldsw + _i * 8192), 16, 0, 0); } while (0)
; #define PG8_LDA(dst, b, h) do { _Pragma("unroll") for (int m = 0; m < 4; ++m) _Pragma("unroll") for (int k = 0; k < 2; ++k) dst[m][k] = *(const PG8_LAS bf16x8*)(lds + PG8_SA(b, h) + aoff + m * 2048 + k * 1024); } while (0)
; #define PG8_LDB(dst, b, h) do { _Pragma("unroll") for (int n = 0; n < 2; ++n) _Pragma("unroll") for (int k = 0; k < 2; ++k) dst[n][k] = *(const PG8_LAS bf16x8*)(lds + PG8_SB(b, h) + boff + n * 2048 + k * 1024); } while (0)
; #define PG8_MMA(ai, bj, At, Bt) do { __builtin_amdgcn_s_setprio(1); _Pragma("unroll") for (int m = 0; m < 4; ++m) _Pragma("unroll") for (int n = 0; n < 2; ++n) _Pragma("unroll") for (int k = 0; k < 2; ++k) \
;         acc[ai][bj][m][n] = __builtin_amdgcn_mfma_f32_16x16x32_bf16(Bt[n][k], At[m][k], acc[ai][bj][m][n], 0, 0, 0); __builtin_amdgcn_s_setprio(0); } while (0)
; #define PG8_WAIT_V(n) asm volatile("s_waitcnt vmcnt(" #n ")" ::: "memory")
; #define PG8_WAIT_L(n) asm volatile("s_waitcnt lgkmcnt(" #n ")" ::: "memory")
; #define PG8_BAR __builtin_amdgcn_s_barrier()
; #define PG8_SCHED __builtin_amdgcn_sched_barrier(0)
; template <class Epi, class Sched, bool ALIGN_EPI = false, bool SP2 = false>
; __device__ __forceinline__ void gemm_phase(PG8_LAS unsigned char* lds, const Gemm g, const Sched& S, const Epi& E, int tid_in) {
;     ...
;             PG8_WAIT_V(8); PG8_WAIT_L(0); PG8_BAR; PG8_MMA(1, 0, At, B0); PG8_MMA(1, 1, At, B1); PG8_BAR; PG8_SCHED;
;             PG8_LDB(B0, 1, 0); PG8_LDB(B1, 1, 1); PG8_SCHED; PG8_LDA(At, 1, 0); PG8_STAGE(PG8_SA(0, 1), a2 + hstep, voffA);
;             PG8_WAIT_V(8); PG8_WAIT_L(0); PG8_BAR; PG8_MMA(0, 0, At, B0); PG8_MMA(0, 1, At, B1); PG8_BAR; PG8_SCHED;
	s_setprio 1
	v_mfma_f32_16x16x32_bf16 v[60:63], v[130:133], v[162:165], v[60:63]
	v_mfma_f32_16x16x32_bf16 v[56:59], v[138:141], v[162:165], v[56:59]
	v_mfma_f32_16x16x32_bf16 v[44:47], v[130:133], v[170:173], v[44:47]
	v_mfma_f32_16x16x32_bf16 v[40:43], v[138:141], v[170:173], v[40:43]
	v_mfma_f32_16x16x32_bf16 v[28:31], v[130:133], v[178:181], v[28:31]
	v_mfma_f32_16x16x32_bf16 v[24:27], v[138:141], v[178:181], v[24:27]
	v_mfma_f32_16x16x32_bf16 v[12:15], v[130:133], v[200:203], v[12:15]
	v_mfma_f32_16x16x32_bf16 v[8:11], v[138:141], v[200:203], v[8:11]
	v_mfma_f32_16x16x32_bf16 v[60:63], v[134:137], v[166:169], v[60:63]
	v_mfma_f32_16x16x32_bf16 v[56:59], v[142:145], v[166:169], v[56:59]
	v_mfma_f32_16x16x32_bf16 v[44:47], v[134:137], v[174:177], v[44:47]
	v_mfma_f32_16x16x32_bf16 v[40:43], v[142:145], v[174:177], v[40:43]
	v_mfma_f32_16x16x32_bf16 v[28:31], v[134:137], v[182:185], v[28:31]
	v_mfma_f32_16x16x32_bf16 v[24:27], v[142:145], v[182:185], v[24:27]
	v_mfma_f32_16x16x32_bf16 v[12:15], v[134:137], v[204:207], v[12:15]
	v_mfma_f32_16x16x32_bf16 v[8:11], v[142:145], v[204:207], v[8:11]
	v_mfma_f32_16x16x32_bf16 v[52:55], v[146:149], v[162:165], v[52:55]
	v_mfma_f32_16x16x32_bf16 v[48:51], v[154:157], v[162:165], v[48:51]
	v_mfma_f32_16x16x32_bf16 v[36:39], v[146:149], v[170:173], v[36:39]
	v_mfma_f32_16x16x32_bf16 v[32:35], v[154:157], v[170:173], v[32:35]
	v_mfma_f32_16x16x32_bf16 v[20:23], v[146:149], v[178:181], v[20:23]
	v_mfma_f32_16x16x32_bf16 v[16:19], v[154:157], v[178:181], v[16:19]
	v_mfma_f32_16x16x32_bf16 v[4:7], v[146:149], v[200:203], v[4:7]
	v_mfma_f32_16x16x32_bf16 v[0:3], v[154:157], v[200:203], v[0:3]
	v_mfma_f32_16x16x32_bf16 v[52:55], v[150:153], v[166:169], v[52:55]
	v_mfma_f32_16x16x32_bf16 v[48:51], v[158:161], v[166:169], v[48:51]
	v_mfma_f32_16x16x32_bf16 v[36:39], v[150:153], v[174:177], v[36:39]
	v_mfma_f32_16x16x32_bf16 v[32:35], v[158:161], v[174:177], v[32:35]
	v_mfma_f32_16x16x32_bf16 v[20:23], v[150:153], v[182:185], v[20:23]
	v_mfma_f32_16x16x32_bf16 v[16:19], v[158:161], v[182:185], v[16:19]
	v_mfma_f32_16x16x32_bf16 v[4:7], v[150:153], v[204:207], v[4:7]
	v_mfma_f32_16x16x32_bf16 v[0:3], v[158:161], v[204:207], v[0:3]
	s_setprio 0
	s_barrier
	s_add_i32 s66, 0, 0x18000
	s_add_i32 s67, 0, 0x1c000
	v_add_u32_e32 v142, s66, v214
	v_add_u32_e32 v158, s67, v214
	ds_read_b128 v[130:133], v142
	ds_read_b128 v[134:137], v142 offset:1024
	ds_read_b128 v[138:141], v142 offset:2048
	ds_read_b128 v[142:145], v142 offset:3072
	ds_read_b128 v[146:149], v158
	ds_read_b128 v[150:153], v158 offset:1024
	ds_read_b128 v[154:157], v158 offset:2048
	ds_read_b128 v[158:161], v158 offset:3072
	s_add_u32 s56, s56, 0x40000
	s_addc_u32 s57, s57, 0
	s_mov_b32 m0, s18
	v_lshl_add_u64 v[226:227], s[56:57], 0, v[190:191]
	ds_read_b128 v[162:165], v215 offset:32768
	ds_read_b128 v[166:169], v215 offset:33792
	ds_read_b128 v[170:173], v215 offset:34816
	ds_read_b128 v[174:177], v215 offset:35840
	ds_read_b128 v[178:181], v215 offset:36864
	ds_read_b128 v[182:185], v215 offset:37888
	ds_read_b128 v[200:203], v215 offset:38912
	ds_read_b128 v[204:207], v215 offset:39936
	global_load_lds_dwordx4 v[226:227], off
	v_lshl_add_u64 v[226:227], s[56:57], 0, v[192:193]
	s_mov_b32 m0, s19
	s_nop 0
	global_load_lds_dwordx4 v[226:227], off
	s_waitcnt vmcnt(8) lgkmcnt(0)
	s_barrier
	s_setprio 1
	v_mfma_f32_16x16x32_bf16 v[126:129], v[130:133], v[162:165], v[126:129]
	v_mfma_f32_16x16x32_bf16 v[122:125], v[138:141], v[162:165], v[122:125]
	v_mfma_f32_16x16x32_bf16 v[110:113], v[130:133], v[170:173], v[110:113]
	v_mfma_f32_16x16x32_bf16 v[106:109], v[138:141], v[170:173], v[106:109]
	v_mfma_f32_16x16x32_bf16 v[94:97], v[130:133], v[178:181], v[94:97]
	v_mfma_f32_16x16x32_bf16 v[90:93], v[138:141], v[178:181], v[90:93]
	v_mfma_f32_16x16x32_bf16 v[76:79], v[130:133], v[200:203], v[76:79]
	v_mfma_f32_16x16x32_bf16 v[72:75], v[138:141], v[200:203], v[72:75]
	v_mfma_f32_16x16x32_bf16 v[126:129], v[134:137], v[166:169], v[126:129]
	v_mfma_f32_16x16x32_bf16 v[122:125], v[142:145], v[166:169], v[122:125]
	v_mfma_f32_16x16x32_bf16 v[110:113], v[134:137], v[174:177], v[110:113]
	v_mfma_f32_16x16x32_bf16 v[106:109], v[142:145], v[174:177], v[106:109]
	v_mfma_f32_16x16x32_bf16 v[94:97], v[134:137], v[182:185], v[94:97]
	v_mfma_f32_16x16x32_bf16 v[90:93], v[142:145], v[182:185], v[90:93]
	v_mfma_f32_16x16x32_bf16 v[76:79], v[134:137], v[204:207], v[76:79]
	v_mfma_f32_16x16x32_bf16 v[72:75], v[142:145], v[204:207], v[72:75]
	v_mfma_f32_16x16x32_bf16 v[118:121], v[146:149], v[162:165], v[118:121]
	v_mfma_f32_16x16x32_bf16 v[114:117], v[154:157], v[162:165], v[114:117]
	v_mfma_f32_16x16x32_bf16 v[102:105], v[146:149], v[170:173], v[102:105]
	v_mfma_f32_16x16x32_bf16 v[98:101], v[154:157], v[170:173], v[98:101]
	v_mfma_f32_16x16x32_bf16 v[86:89], v[146:149], v[178:181], v[86:89]
	v_mfma_f32_16x16x32_bf16 v[82:85], v[154:157], v[178:181], v[82:85]
	v_mfma_f32_16x16x32_bf16 v[68:71], v[146:149], v[200:203], v[68:71]
	v_mfma_f32_16x16x32_bf16 v[64:67], v[154:157], v[200:203], v[64:67]
	v_mfma_f32_16x16x32_bf16 v[118:121], v[150:153], v[166:169], v[118:121]
	v_mfma_f32_16x16x32_bf16 v[114:117], v[158:161], v[166:169], v[114:117]
	v_mfma_f32_16x16x32_bf16 v[102:105], v[150:153], v[174:177], v[102:105]
	v_mfma_f32_16x16x32_bf16 v[98:101], v[158:161], v[174:177], v[98:101]
	v_mfma_f32_16x16x32_bf16 v[86:89], v[150:153], v[182:185], v[86:89]
	v_mfma_f32_16x16x32_bf16 v[82:85], v[158:161], v[182:185], v[82:85]
	v_mfma_f32_16x16x32_bf16 v[68:71], v[150:153], v[204:207], v[68:71]
	v_mfma_f32_16x16x32_bf16 v[64:67], v[158:161], v[204:207], v[64:67]
	s_setprio 0
	s_barrier
; #define PG8_STAGE(bufoff, gbase, voff) do { _Pragma("unroll") for (int _i = 0; _i < 2; ++_i) \
;         __builtin_amdgcn_global_load_lds((const unsigned*)((const char*)(gbase) + (voff)[_i]), (PG8_LAS unsigned*)(lds + (bufoff) + ldsw + _i * 8192), 16, 0, 0); } while (0)
; #define PG8_LDA(dst, b, h) do { _Pragma("unroll") for (int m = 0; m < 4; ++m) _Pragma("unroll") for (int k = 0; k < 2; ++k) dst[m][k] = *(const PG8_LAS bf16x8*)(lds + PG8_SA(b, h) + aoff + m * 2048 + k * 1024); } while (0)
; #define PG8_MMA(ai, bj, At, Bt) do { __builtin_amdgcn_s_setprio(1); _Pragma("unroll") for (int m = 0; m < 4; ++m) _Pragma("unroll") for (int n = 0; n < 2; ++n) _Pragma("unroll") for (int k = 0; k < 2; ++k) \
;         acc[ai][bj][m][n] = __builtin_amdgcn_mfma_f32_16x16x32_bf16(Bt[n][k], At[m][k], acc[ai][bj][m][n], 0, 0, 0); __builtin_amdgcn_s_setprio(0); } while (0)
; #define PG8_WAIT_V(n) asm volatile("s_waitcnt vmcnt(" #n ")" ::: "memory")
; #define PG8_WAIT_L(n) asm volatile("s_waitcnt lgkmcnt(" #n ")" ::: "memory")
; #define PG8_BAR __builtin_amdgcn_s_barrier()
; #define PG8_SCHED __builtin_amdgcn_sched_barrier(0)
; template <class Epi, class Sched, bool ALIGN_EPI = false, bool SP2 = false>
; __device__ __forceinline__ void gemm_phase(PG8_LAS unsigned char* lds, const Gemm g, const Sched& S, const Epi& E, int tid_in) {
;     ...
;         for (int t = 0; t < nt; t += 2) {
;             const bool last = (t == nt - 2);
;             const char* a1 = cA + (size_t)(t + 1) * kstep;
;             const char* a2 = last ? nA : cA + (size_t)(t + 2) * kstep; const char* b2 = last ? nB : cB + (size_t)(t + 2) * kstep;
;     ...
;             PG8_LDA(At, 1, 1); PG8_STAGE(PG8_SB(1, 0), b3, voffB); PG8_STAGE(PG8_SB(1, 1), b3 + hstep, voffB); PG8_STAGE(PG8_SA(1, 0), a3, voffA);
;             PG8_WAIT_V(8); PG8_WAIT_L(0); PG8_BAR; PG8_MMA(1, 0, At, B0); PG8_MMA(1, 1, At, B1); PG8_BAR; PG8_SCHED;
	s_add_i32 s56, s66, s15
	v_lshl_add_u64 v[186:187], v[186:187], 0, s[6:7]
	s_mov_b32 m0, s56
	ds_read_b128 v[162:165], v215 offset:49152
	ds_read_b128 v[166:169], v215 offset:50176
	ds_read_b128 v[170:173], v215 offset:51200
	ds_read_b128 v[174:177], v215 offset:52224
	ds_read_b128 v[178:181], v215 offset:53248
	ds_read_b128 v[182:185], v215 offset:54272
	ds_read_b128 v[200:203], v215 offset:55296
	ds_read_b128 v[204:207], v215 offset:56320
	global_load_lds_dwordx4 v[186:187], off
	s_add_i32 m0, s56, 0x2000
	s_add_u32 s54, s54, 0x40080
	v_lshl_add_u64 v[186:187], v[188:189], 0, s[6:7]
	s_addc_u32 s55, s55, 0
	s_add_i32 s56, s67, s15
	global_load_lds_dwordx4 v[186:187], off
	v_lshl_add_u64 v[186:187], s[54:55], 0, v[80:81]
	s_mov_b32 m0, s56
	s_nop 0
	global_load_lds_dwordx4 v[186:187], off
	v_lshl_add_u64 v[186:187], s[54:55], 0, v[194:195]
	s_add_i32 m0, s56, 0x2000
	s_nop 0
	global_load_lds_dwordx4 v[186:187], off
	v_lshl_add_u64 v[186:187], v[208:209], 0, s[6:7]
	s_mov_b32 m0, s58
	s_nop 0
	global_load_lds_dwordx4 v[186:187], off
	v_lshl_add_u64 v[186:187], v[210:211], 0, s[6:7]
	s_mov_b32 m0, s59
	s_nop 0
	global_load_lds_dwordx4 v[186:187], off
	s_waitcnt vmcnt(8) lgkmcnt(0)
	s_barrier
	s_setprio 1
	v_mfma_f32_16x16x32_bf16 v[60:63], v[130:133], v[162:165], v[60:63]
	v_mfma_f32_16x16x32_bf16 v[56:59], v[138:141], v[162:165], v[56:59]
	v_mfma_f32_16x16x32_bf16 v[44:47], v[130:133], v[170:173], v[44:47]
	v_mfma_f32_16x16x32_bf16 v[40:43], v[138:141], v[170:173], v[40:43]
	v_mfma_f32_16x16x32_bf16 v[28:31], v[130:133], v[178:181], v[28:31]
	v_mfma_f32_16x16x32_bf16 v[24:27], v[138:141], v[178:181], v[24:27]
	v_mfma_f32_16x16x32_bf16 v[12:15], v[130:133], v[200:203], v[12:15]
	v_mfma_f32_16x16x32_bf16 v[8:11], v[138:141], v[200:203], v[8:11]
	v_mfma_f32_16x16x32_bf16 v[60:63], v[134:137], v[166:169], v[60:63]
	v_mfma_f32_16x16x32_bf16 v[56:59], v[142:145], v[166:169], v[56:59]
	v_mfma_f32_16x16x32_bf16 v[44:47], v[134:137], v[174:177], v[44:47]
	v_mfma_f32_16x16x32_bf16 v[40:43], v[142:145], v[174:177], v[40:43]
	v_mfma_f32_16x16x32_bf16 v[28:31], v[134:137], v[182:185], v[28:31]
	v_mfma_f32_16x16x32_bf16 v[24:27], v[142:145], v[182:185], v[24:27]
	v_mfma_f32_16x16x32_bf16 v[12:15], v[134:137], v[204:207], v[12:15]
	v_mfma_f32_16x16x32_bf16 v[8:11], v[142:145], v[204:207], v[8:11]
	v_mfma_f32_16x16x32_bf16 v[52:55], v[146:149], v[162:165], v[52:55]
	v_mfma_f32_16x16x32_bf16 v[48:51], v[154:157], v[162:165], v[48:51]
	v_mfma_f32_16x16x32_bf16 v[36:39], v[146:149], v[170:173], v[36:39]
	v_mfma_f32_16x16x32_bf16 v[32:35], v[154:157], v[170:173], v[32:35]
	v_mfma_f32_16x16x32_bf16 v[20:23], v[146:149], v[178:181], v[20:23]
	v_mfma_f32_16x16x32_bf16 v[16:19], v[154:157], v[178:181], v[16:19]
	v_mfma_f32_16x16x32_bf16 v[4:7], v[146:149], v[200:203], v[4:7]
	v_mfma_f32_16x16x32_bf16 v[0:3], v[154:157], v[200:203], v[0:3]
	v_mfma_f32_16x16x32_bf16 v[52:55], v[150:153], v[166:169], v[52:55]
	v_mfma_f32_16x16x32_bf16 v[48:51], v[158:161], v[166:169], v[48:51]
	v_mfma_f32_16x16x32_bf16 v[36:39], v[150:153], v[174:177], v[36:39]
	v_mfma_f32_16x16x32_bf16 v[32:35], v[158:161], v[174:177], v[32:35]
	v_mfma_f32_16x16x32_bf16 v[20:23], v[150:153], v[182:185], v[20:23]
	v_mfma_f32_16x16x32_bf16 v[16:19], v[158:161], v[182:185], v[16:19]
	v_mfma_f32_16x16x32_bf16 v[4:7], v[150:153], v[204:207], v[4:7]
	v_mfma_f32_16x16x32_bf16 v[0:3], v[158:161], v[204:207], v[0:3]
	s_setprio 0
	s_barrier
	s_add_i32 s65, s65, 2
	s_add_u32 s52, s52, 0x100
	s_addc_u32 s53, s53, 0
	s_add_u32 s63, s63, 0x100
	s_addc_u32 s64, s64, 0
	s_cmp_gt_u32 s65, 13
	s_cbranch_scc0 .LBB0_1340
	s_and_b64 vcc, exec, s[8:9]
	s_cbranch_vccz .LBB0_1343
	s_barrier

; #define PG8_STAGE(bufoff, gbase, voff) do { _Pragma("unroll") for (int _i = 0; _i < 2; ++_i) \
;         __builtin_amdgcn_global_load_lds((const unsigned*)((const char*)(gbase) + (voff)[_i]), (PG8_LAS unsigned*)(lds + (bufoff) + ldsw + _i * 8192), 16, 0, 0); } while (0)
; #define PG8_LDA(dst, b, h) do { _Pragma("unroll") for (int m = 0; m < 4; ++m) _Pragma("unroll") for (int k = 0; k < 2; ++k) dst[m][k] = *(const PG8_LAS bf16x8*)(lds + PG8_SA(b, h) + aoff + m * 2048 + k * 1024); } while (0)
; #define PG8_LDB(dst, b, h) do { _Pragma("unroll") for (int n = 0; n < 2; ++n) _Pragma("unroll") for (int k = 0; k < 2; ++k) dst[n][k] = *(const PG8_LAS bf16x8*)(lds + PG8_SB(b, h) + boff + n * 2048 + k * 1024); } while (0)
; #define PG8_MMA(ai, bj, At, Bt) do { __builtin_amdgcn_s_setprio(1); _Pragma("unroll") for (int m = 0; m < 4; ++m) _Pragma("unroll") for (int n = 0; n < 2; ++n) _Pragma("unroll") for (int k = 0; k < 2; ++k) \
;         acc[ai][bj][m][n] = __builtin_amdgcn_mfma_f32_16x16x32_bf16(Bt[n][k], At[m][k], acc[ai][bj][m][n], 0, 0, 0); __builtin_amdgcn_s_setprio(0); } while (0)
; #define PG8_WAIT_V(n) asm volatile("s_waitcnt vmcnt(" #n ")" ::: "memory")
; #define PG8_BAR __builtin_amdgcn_s_barrier()
; template <class Epi, class Sched, bool ALIGN_EPI = false, bool SP2 = false>
; __device__ __forceinline__ void gemm_phase(PG8_LAS unsigned char* lds, const Gemm g, const Sched& S, const Epi& E, int tid_in) {
;     ...
;         for (int t = 0; t < nt; t += 2) {
;             const bool last = (t == nt - 2);
;             const char* a1 = cA + (size_t)(t + 1) * kstep;
;             const char* a2 = last ? nA : cA + (size_t)(t + 2) * kstep; const char* b2 = last ? nB : cB + (size_t)(t + 2) * kstep;
;             const char* a3 = a2 + kstep; const char* b3 = b2 + kstep;
;             if (last && has_next) S.a_ready(nxt);
;             if constexpr (SP2) {
;             PG8_LDB(B0, 0, 0); PG8_LDB(B1, 0, 1); PG8_SCHED; PG8_LDA(At, 0, 0); PG8_STAGE(PG8_SA(1, 1), a1 + hstep, voffA);
;             PG8_WAIT_V(8); PG8_WAIT_L(0); PG8_BAR; PG8_MMA(0, 0, At, B0); PG8_MMA(0, 1, At, B1); PG8_BAR; PG8_SCHED;
;             PG8_LDA(At, 0, 1); PG8_STAGE(PG8_SB(0, 0), b2, voffB); PG8_STAGE(PG8_SB(0, 1), b2 + hstep, voffB); PG8_STAGE(PG8_SA(0, 0), a2, voffA);
;             PG8_WAIT_V(8); PG8_WAIT_L(0); PG8_BAR; PG8_MMA(1, 0, At, B0); PG8_MMA(1, 1, At, B1); PG8_BAR; PG8_SCHED;
.LBB0_1432:
	s_add_u32 s42, s40, 0xfffc0080
	s_addc_u32 s43, s41, -1
	s_add_i32 s79, 0, 0x10000
	s_cmp_eq_u32 s78, 12
	s_cselect_b32 s67, s0, s43
	s_cselect_b32 s66, s1, s42
	s_cselect_b32 s43, s5, s77
	s_cselect_b32 s42, s59, s61
	s_add_i32 s82, 0, 0x14000
	v_add_u32_e32 v142, s79, v210
	v_add_u32_e32 v158, s82, v210
	ds_read_b128 v[114:117], v142
	ds_read_b128 v[118:121], v142 offset:1024
	ds_read_b128 v[138:141], v142 offset:2048
	ds_read_b128 v[142:145], v142 offset:3072
	ds_read_b128 v[146:149], v158
	ds_read_b128 v[150:153], v158 offset:1024
	ds_read_b128 v[154:157], v158 offset:2048
	ds_read_b128 v[158:161], v158 offset:3072
	v_lshl_add_u64 v[184:185], s[40:41], 0, v[168:169]
	s_add_i32 m0, s9, 0xc000
	ds_read_b128 v[172:175], v211
	ds_read_b128 v[176:179], v211 offset:1024
	ds_read_b128 v[180:183], v211 offset:2048
	ds_read_b128 v[190:193], v211 offset:3072
	ds_read_b128 v[194:197], v211 offset:4096
	ds_read_b128 v[198:201], v211 offset:5120
	ds_read_b128 v[202:205], v211 offset:6144
	ds_read_b128 v[212:215], v211 offset:7168
	global_load_lds_dwordx4 v[184:185], off
	v_lshl_add_u64 v[184:185], s[40:41], 0, v[170:171]
	s_add_i32 m0, s9, 0xe000
	s_nop 0
	global_load_lds_dwordx4 v[184:185], off
	s_waitcnt vmcnt(8) lgkmcnt(0)
	s_barrier
	s_setprio 1
	v_mfma_f32_16x16x32_bf16 v[134:137], v[114:117], v[172:175], v[134:137]
	v_mfma_f32_16x16x32_bf16 v[130:133], v[138:141], v[172:175], v[130:133]
	v_mfma_f32_16x16x32_bf16 v[110:113], v[114:117], v[180:183], v[110:113]
	v_mfma_f32_16x16x32_bf16 v[106:109], v[138:141], v[180:183], v[106:109]
	v_mfma_f32_16x16x32_bf16 v[94:97], v[114:117], v[194:197], v[94:97]
	v_mfma_f32_16x16x32_bf16 v[90:93], v[138:141], v[194:197], v[90:93]
	v_mfma_f32_16x16x32_bf16 v[76:79], v[114:117], v[202:205], v[76:79]
	v_mfma_f32_16x16x32_bf16 v[72:75], v[138:141], v[202:205], v[72:75]
	v_mfma_f32_16x16x32_bf16 v[134:137], v[118:121], v[176:179], v[134:137]
	v_mfma_f32_16x16x32_bf16 v[130:133], v[142:145], v[176:179], v[130:133]
	v_mfma_f32_16x16x32_bf16 v[110:113], v[118:121], v[190:193], v[110:113]
	v_mfma_f32_16x16x32_bf16 v[106:109], v[142:145], v[190:193], v[106:109]
	v_mfma_f32_16x16x32_bf16 v[94:97], v[118:121], v[198:201], v[94:97]
	v_mfma_f32_16x16x32_bf16 v[90:93], v[142:145], v[198:201], v[90:93]
	v_mfma_f32_16x16x32_bf16 v[76:79], v[118:121], v[212:215], v[76:79]
	v_mfma_f32_16x16x32_bf16 v[72:75], v[142:145], v[212:215], v[72:75]
	v_mfma_f32_16x16x32_bf16 v[126:129], v[146:149], v[172:175], v[126:129]
	v_mfma_f32_16x16x32_bf16 v[122:125], v[154:157], v[172:175], v[122:125]
	v_mfma_f32_16x16x32_bf16 v[102:105], v[146:149], v[180:183], v[102:105]
	v_mfma_f32_16x16x32_bf16 v[98:101], v[154:157], v[180:183], v[98:101]
	v_mfma_f32_16x16x32_bf16 v[86:89], v[146:149], v[194:197], v[86:89]
	v_mfma_f32_16x16x32_bf16 v[82:85], v[154:157], v[194:197], v[82:85]
	v_mfma_f32_16x16x32_bf16 v[68:71], v[146:149], v[202:205], v[68:71]
	v_mfma_f32_16x16x32_bf16 v[64:67], v[154:157], v[202:205], v[64:67]
	v_mfma_f32_16x16x32_bf16 v[126:129], v[150:153], v[176:179], v[126:129]
	v_mfma_f32_16x16x32_bf16 v[122:125], v[158:161], v[176:179], v[122:125]
	v_mfma_f32_16x16x32_bf16 v[102:105], v[150:153], v[190:193], v[102:105]
	v_mfma_f32_16x16x32_bf16 v[98:101], v[158:161], v[190:193], v[98:101]
	v_mfma_f32_16x16x32_bf16 v[86:89], v[150:153], v[198:201], v[86:89]
	v_mfma_f32_16x16x32_bf16 v[82:85], v[158:161], v[198:201], v[82:85]
	v_mfma_f32_16x16x32_bf16 v[68:71], v[150:153], v[212:215], v[68:71]
	v_mfma_f32_16x16x32_bf16 v[64:67], v[158:161], v[212:215], v[64:67]
	s_setprio 0
	s_barrier
	s_add_i32 s79, s79, s14
	v_lshl_add_u64 v[184:185], s[42:43], 0, v[80:81]
	s_mov_b32 m0, s79
	ds_read_b128 v[172:175], v211 offset:16384
	ds_read_b128 v[176:179], v211 offset:17408
	ds_read_b128 v[180:183], v211 offset:18432
	ds_read_b128 v[190:193], v211 offset:19456
	ds_read_b128 v[194:197], v211 offset:20480
	ds_read_b128 v[198:201], v211 offset:21504
	ds_read_b128 v[202:205], v211 offset:22528
	ds_read_b128 v[212:215], v211 offset:23552
	global_load_lds_dwordx4 v[184:185], off
	s_add_i32 m0, s79, 0x2000
	s_add_u32 s80, s42, 0x40000
	v_lshl_add_u64 v[186:187], s[42:43], 0, v[166:167]
	s_addc_u32 s81, s43, 0
	s_add_i32 s79, s82, s14
	global_load_lds_dwordx4 v[186:187], off
	v_lshl_add_u64 v[188:189], s[80:81], 0, v[80:81]
	s_mov_b32 m0, s79
	v_lshl_add_u64 v[206:207], s[66:67], 0, v[164:165]
	global_load_lds_dwordx4 v[188:189], off
	v_lshl_add_u64 v[188:189], s[80:81], 0, v[166:167]
	s_add_i32 m0, s79, 0x2000
	s_nop 0
	global_load_lds_dwordx4 v[188:189], off
	v_lshl_add_u64 v[188:189], s[66:67], 0, v[162:163]
	s_mov_b32 m0, s9
	s_nop 0
	global_load_lds_dwordx4 v[188:189], off
	s_mov_b32 m0, s15
	s_nop 0
	global_load_lds_dwordx4 v[206:207], off
	s_waitcnt vmcnt(8) lgkmcnt(0)
	s_barrier
; #define PG8_STAGE(bufoff, gbase, voff) do { _Pragma("unroll") for (int _i = 0; _i < 2; ++_i) \
;         __builtin_amdgcn_global_load_lds((const unsigned*)((const char*)(gbase) + (voff)[_i]), (PG8_LAS unsigned*)(lds + (bufoff) + ldsw + _i * 8192), 16, 0, 0); } while (0)
; #define PG8_LDA(dst, b, h) do { _Pragma("unroll") for (int m = 0; m < 4; ++m) _Pragma("unroll") for (int k = 0; k < 2; ++k) dst[m][k] = *(const PG8_LAS bf16x8*)(lds + PG8_SA(b, h) + aoff + m * 2048 + k * 1024); } while (0)
; #define PG8_LDB(dst, b, h) do { _Pragma("unroll") for (int n = 0; n < 2; ++n) _Pragma("unroll") for (int k = 0; k < 2; ++k) dst[n][k] = *(const PG8_LAS bf16x8*)(lds + PG8_SB(b, h) + boff + n * 2048 + k * 1024); } while (0)
; #define PG8_MMA(ai, bj, At, Bt) do { __builtin_amdgcn_s_setprio(1); _Pragma("unroll") for (int m = 0; m < 4; ++m) _Pragma("unroll") for (int n = 0; n < 2; ++n) _Pragma("unroll") for (int k = 0; k < 2; ++k) \
;         acc[ai][bj][m][n] = __builtin_amdgcn_mfma_f32_16x16x32_bf16(Bt[n][k], At[m][k], acc[ai][bj][m][n], 0, 0, 0); __builtin_amdgcn_s_setprio(0); } while (0)
; #define PG8_WAIT_V(n) asm volatile("s_waitcnt vmcnt(" #n ")" ::: "memory")
; #define PG8_WAIT_L(n) asm volatile("s_waitcnt lgkmcnt(" #n ")" ::: "memory")
; #define PG8_BAR __builtin_amdgcn_s_barrier()
; #define PG8_SCHED __builtin_amdgcn_sched_barrier(0)
; template <class Epi, class Sched, bool ALIGN_EPI = false, bool SP2 = false>
; __device__ __forceinline__ void gemm_phase(PG8_LAS unsigned char* lds, const Gemm g, const Sched& S, const Epi& E, int tid_in) {
;     ...
;             PG8_WAIT_V(8); PG8_WAIT_L(0); PG8_BAR; PG8_MMA(1, 0, At, B0); PG8_MMA(1, 1, At, B1); PG8_BAR; PG8_SCHED;
;             PG8_LDB(B0, 1, 0); PG8_LDB(B1, 1, 1); PG8_SCHED; PG8_LDA(At, 1, 0); PG8_STAGE(PG8_SA(0, 1), a2 + hstep, voffA);
;             PG8_WAIT_V(8); PG8_WAIT_L(0); PG8_BAR; PG8_MMA(0, 0, At, B0); PG8_MMA(0, 1, At, B1); PG8_BAR; PG8_SCHED;
	s_setprio 1
	v_mfma_f32_16x16x32_bf16 v[60:63], v[114:117], v[172:175], v[60:63]
	v_mfma_f32_16x16x32_bf16 v[56:59], v[138:141], v[172:175], v[56:59]
	v_mfma_f32_16x16x32_bf16 v[44:47], v[114:117], v[180:183], v[44:47]
	v_mfma_f32_16x16x32_bf16 v[40:43], v[138:141], v[180:183], v[40:43]
	v_mfma_f32_16x16x32_bf16 v[28:31], v[114:117], v[194:197], v[28:31]
	v_mfma_f32_16x16x32_bf16 v[24:27], v[138:141], v[194:197], v[24:27]
	v_mfma_f32_16x16x32_bf16 v[12:15], v[114:117], v[202:205], v[12:15]
	v_mfma_f32_16x16x32_bf16 v[8:11], v[138:141], v[202:205], v[8:11]
	v_mfma_f32_16x16x32_bf16 v[60:63], v[118:121], v[176:179], v[60:63]
	v_mfma_f32_16x16x32_bf16 v[56:59], v[142:145], v[176:179], v[56:59]
	v_mfma_f32_16x16x32_bf16 v[44:47], v[118:121], v[190:193], v[44:47]
	v_mfma_f32_16x16x32_bf16 v[40:43], v[142:145], v[190:193], v[40:43]
	v_mfma_f32_16x16x32_bf16 v[28:31], v[118:121], v[198:201], v[28:31]
	v_mfma_f32_16x16x32_bf16 v[24:27], v[142:145], v[198:201], v[24:27]
	v_mfma_f32_16x16x32_bf16 v[12:15], v[118:121], v[212:215], v[12:15]
	v_mfma_f32_16x16x32_bf16 v[8:11], v[142:145], v[212:215], v[8:11]
	v_mfma_f32_16x16x32_bf16 v[52:55], v[146:149], v[172:175], v[52:55]
	v_mfma_f32_16x16x32_bf16 v[48:51], v[154:157], v[172:175], v[48:51]
	v_mfma_f32_16x16x32_bf16 v[36:39], v[146:149], v[180:183], v[36:39]
	v_mfma_f32_16x16x32_bf16 v[32:35], v[154:157], v[180:183], v[32:35]
	v_mfma_f32_16x16x32_bf16 v[20:23], v[146:149], v[194:197], v[20:23]
	v_mfma_f32_16x16x32_bf16 v[16:19], v[154:157], v[194:197], v[16:19]
	v_mfma_f32_16x16x32_bf16 v[4:7], v[146:149], v[202:205], v[4:7]
	v_mfma_f32_16x16x32_bf16 v[0:3], v[154:157], v[202:205], v[0:3]
	v_mfma_f32_16x16x32_bf16 v[52:55], v[150:153], v[176:179], v[52:55]
	v_mfma_f32_16x16x32_bf16 v[48:51], v[158:161], v[176:179], v[48:51]
	v_mfma_f32_16x16x32_bf16 v[36:39], v[150:153], v[190:193], v[36:39]
	v_mfma_f32_16x16x32_bf16 v[32:35], v[158:161], v[190:193], v[32:35]
	v_mfma_f32_16x16x32_bf16 v[20:23], v[150:153], v[198:201], v[20:23]
	v_mfma_f32_16x16x32_bf16 v[16:19], v[158:161], v[198:201], v[16:19]
	v_mfma_f32_16x16x32_bf16 v[4:7], v[150:153], v[212:215], v[4:7]
	v_mfma_f32_16x16x32_bf16 v[0:3], v[158:161], v[212:215], v[0:3]
	s_setprio 0
	s_barrier
	s_add_i32 s79, 0, 0x18000
	s_add_i32 s80, 0, 0x1c000
	v_add_u32_e32 v142, s79, v210
	v_add_u32_e32 v158, s80, v210
	ds_read_b128 v[114:117], v142
	ds_read_b128 v[118:121], v142 offset:1024
	ds_read_b128 v[138:141], v142 offset:2048
	ds_read_b128 v[142:145], v142 offset:3072
	ds_read_b128 v[146:149], v158
	ds_read_b128 v[150:153], v158 offset:1024
	ds_read_b128 v[154:157], v158 offset:2048
	ds_read_b128 v[158:161], v158 offset:3072
	s_add_u32 s66, s66, 0x40000
	s_addc_u32 s67, s67, 0
	s_mov_b32 m0, s16
	v_lshl_add_u64 v[226:227], s[66:67], 0, v[162:163]
	ds_read_b128 v[172:175], v211 offset:32768
	ds_read_b128 v[176:179], v211 offset:33792
	ds_read_b128 v[180:183], v211 offset:34816
	ds_read_b128 v[190:193], v211 offset:35840
	ds_read_b128 v[194:197], v211 offset:36864
	ds_read_b128 v[198:201], v211 offset:37888
	ds_read_b128 v[202:205], v211 offset:38912
	ds_read_b128 v[212:215], v211 offset:39936
	global_load_lds_dwordx4 v[226:227], off
	v_lshl_add_u64 v[226:227], s[66:67], 0, v[164:165]
	s_mov_b32 m0, s17
	s_nop 0
	global_load_lds_dwordx4 v[226:227], off
	s_waitcnt vmcnt(8) lgkmcnt(0)
	s_barrier
	s_setprio 1
	v_mfma_f32_16x16x32_bf16 v[134:137], v[114:117], v[172:175], v[134:137]
	v_mfma_f32_16x16x32_bf16 v[130:133], v[138:141], v[172:175], v[130:133]
	v_mfma_f32_16x16x32_bf16 v[110:113], v[114:117], v[180:183], v[110:113]
	v_mfma_f32_16x16x32_bf16 v[106:109], v[138:141], v[180:183], v[106:109]
	v_mfma_f32_16x16x32_bf16 v[94:97], v[114:117], v[194:197], v[94:97]
	v_mfma_f32_16x16x32_bf16 v[90:93], v[138:141], v[194:197], v[90:93]
	v_mfma_f32_16x16x32_bf16 v[76:79], v[114:117], v[202:205], v[76:79]
	v_mfma_f32_16x16x32_bf16 v[72:75], v[138:141], v[202:205], v[72:75]
	v_mfma_f32_16x16x32_bf16 v[134:137], v[118:121], v[176:179], v[134:137]
	v_mfma_f32_16x16x32_bf16 v[130:133], v[142:145], v[176:179], v[130:133]
	v_mfma_f32_16x16x32_bf16 v[110:113], v[118:121], v[190:193], v[110:113]
	v_mfma_f32_16x16x32_bf16 v[106:109], v[142:145], v[190:193], v[106:109]
	v_mfma_f32_16x16x32_bf16 v[94:97], v[118:121], v[198:201], v[94:97]
	v_mfma_f32_16x16x32_bf16 v[90:93], v[142:145], v[198:201], v[90:93]
	v_mfma_f32_16x16x32_bf16 v[76:79], v[118:121], v[212:215], v[76:79]
	v_mfma_f32_16x16x32_bf16 v[72:75], v[142:145], v[212:215], v[72:75]
	v_mfma_f32_16x16x32_bf16 v[126:129], v[146:149], v[172:175], v[126:129]
	v_mfma_f32_16x16x32_bf16 v[122:125], v[154:157], v[172:175], v[122:125]
	v_mfma_f32_16x16x32_bf16 v[102:105], v[146:149], v[180:183], v[102:105]
	v_mfma_f32_16x16x32_bf16 v[98:101], v[154:157], v[180:183], v[98:101]
	v_mfma_f32_16x16x32_bf16 v[86:89], v[146:149], v[194:197], v[86:89]
	v_mfma_f32_16x16x32_bf16 v[82:85], v[154:157], v[194:197], v[82:85]
	v_mfma_f32_16x16x32_bf16 v[68:71], v[146:149], v[202:205], v[68:71]
	v_mfma_f32_16x16x32_bf16 v[64:67], v[154:157], v[202:205], v[64:67]
	v_mfma_f32_16x16x32_bf16 v[126:129], v[150:153], v[176:179], v[126:129]
	v_mfma_f32_16x16x32_bf16 v[122:125], v[158:161], v[176:179], v[122:125]
	v_mfma_f32_16x16x32_bf16 v[102:105], v[150:153], v[190:193], v[102:105]
	v_mfma_f32_16x16x32_bf16 v[98:101], v[158:161], v[190:193], v[98:101]
	v_mfma_f32_16x16x32_bf16 v[86:89], v[150:153], v[198:201], v[86:89]
	v_mfma_f32_16x16x32_bf16 v[82:85], v[158:161], v[198:201], v[82:85]
	v_mfma_f32_16x16x32_bf16 v[68:71], v[150:153], v[212:215], v[68:71]
	v_mfma_f32_16x16x32_bf16 v[64:67], v[158:161], v[212:215], v[64:67]
	s_setprio 0
	s_barrier
; #define PG8_STAGE(bufoff, gbase, voff) do { _Pragma("unroll") for (int _i = 0; _i < 2; ++_i) \
;         __builtin_amdgcn_global_load_lds((const unsigned*)((const char*)(gbase) + (voff)[_i]), (PG8_LAS unsigned*)(lds + (bufoff) + ldsw + _i * 8192), 16, 0, 0); } while (0)
; #define PG8_LDA(dst, b, h) do { _Pragma("unroll") for (int m = 0; m < 4; ++m) _Pragma("unroll") for (int k = 0; k < 2; ++k) dst[m][k] = *(const PG8_LAS bf16x8*)(lds + PG8_SA(b, h) + aoff + m * 2048 + k * 1024); } while (0)
; #define PG8_LDB(dst, b, h) do { _Pragma("unroll") for (int n = 0; n < 2; ++n) _Pragma("unroll") for (int k = 0; k < 2; ++k) dst[n][k] = *(const PG8_LAS bf16x8*)(lds + PG8_SB(b, h) + boff + n * 2048 + k * 1024); } while (0)
; #define PG8_MMA(ai, bj, At, Bt) do { __builtin_amdgcn_s_setprio(1); _Pragma("unroll") for (int m = 0; m < 4; ++m) _Pragma("unroll") for (int n = 0; n < 2; ++n) _Pragma("unroll") for (int k = 0; k < 2; ++k) \
;         acc[ai][bj][m][n] = __builtin_amdgcn_mfma_f32_16x16x32_bf16(Bt[n][k], At[m][k], acc[ai][bj][m][n], 0, 0, 0); __builtin_amdgcn_s_setprio(0); } while (0)
; #define PG8_WAIT_V(n) asm volatile("s_waitcnt vmcnt(" #n ")" ::: "memory")
; #define PG8_WAIT_L(n) asm volatile("s_waitcnt lgkmcnt(" #n ")" ::: "memory")
; #define PG8_BAR __builtin_amdgcn_s_barrier()
; #define PG8_SCHED __builtin_amdgcn_sched_barrier(0)
; template <class Epi, class Sched, bool ALIGN_EPI = false, bool SP2 = false>
; __device__ __forceinline__ void gemm_phase(PG8_LAS unsigned char* lds, const Gemm g, const Sched& S, const Epi& E, int tid_in) {
;     ...
;             PG8_LDB(B0, 1, 0); PG8_LDB(B1, 1, 1); PG8_SCHED; PG8_LDA(At, 1, 0); PG8_STAGE(PG8_SA(0, 1), a2 + hstep, voffA);
;             PG8_WAIT_V(8); PG8_WAIT_L(0); PG8_BAR; PG8_MMA(0, 0, At, B0); PG8_MMA(0, 1, At, B1); PG8_BAR; PG8_SCHED;
;             PG8_LDA(At, 1, 1); PG8_STAGE(PG8_SB(1, 0), b3, voffB); PG8_STAGE(PG8_SB(1, 1), b3 + hstep, voffB); PG8_STAGE(PG8_SA(1, 0), a3, voffA);
;             PG8_WAIT_V(8); PG8_WAIT_L(0); PG8_BAR; PG8_MMA(1, 0, At, B0); PG8_MMA(1, 1, At, B1); PG8_BAR; PG8_SCHED;
;     ...
;         if constexpr (ALIGN_EPI) { if (wr == 0) PG8_BAR; }
	s_add_i32 s66, s79, s14
	v_lshl_add_u64 v[184:185], v[184:185], 0, s[6:7]
	s_mov_b32 m0, s66
	ds_read_b128 v[172:175], v211 offset:49152
	ds_read_b128 v[176:179], v211 offset:50176
	ds_read_b128 v[180:183], v211 offset:51200
	ds_read_b128 v[190:193], v211 offset:52224
	ds_read_b128 v[194:197], v211 offset:53248
	ds_read_b128 v[198:201], v211 offset:54272
	ds_read_b128 v[202:205], v211 offset:55296
	ds_read_b128 v[212:215], v211 offset:56320
	global_load_lds_dwordx4 v[184:185], off
	s_add_i32 m0, s66, 0x2000
	s_add_u32 s42, s42, 0x40080
	v_lshl_add_u64 v[184:185], v[186:187], 0, s[6:7]
	s_addc_u32 s43, s43, 0
	s_add_i32 s66, s80, s14
	global_load_lds_dwordx4 v[184:185], off
	v_lshl_add_u64 v[184:185], s[42:43], 0, v[80:81]
	s_mov_b32 m0, s66
	s_nop 0
	global_load_lds_dwordx4 v[184:185], off
	v_lshl_add_u64 v[184:185], s[42:43], 0, v[166:167]
	s_add_i32 m0, s66, 0x2000
	s_nop 0
	global_load_lds_dwordx4 v[184:185], off
	v_lshl_add_u64 v[184:185], v[188:189], 0, s[6:7]
	s_mov_b32 m0, s69
	s_nop 0
	global_load_lds_dwordx4 v[184:185], off
	v_lshl_add_u64 v[184:185], v[206:207], 0, s[6:7]
	s_mov_b32 m0, s70
	s_nop 0
	global_load_lds_dwordx4 v[184:185], off
	s_waitcnt vmcnt(8) lgkmcnt(0)
	s_barrier
	s_setprio 1
	v_mfma_f32_16x16x32_bf16 v[60:63], v[114:117], v[172:175], v[60:63]
	v_mfma_f32_16x16x32_bf16 v[56:59], v[138:141], v[172:175], v[56:59]
	v_mfma_f32_16x16x32_bf16 v[44:47], v[114:117], v[180:183], v[44:47]
	v_mfma_f32_16x16x32_bf16 v[40:43], v[138:141], v[180:183], v[40:43]
	v_mfma_f32_16x16x32_bf16 v[28:31], v[114:117], v[194:197], v[28:31]
	v_mfma_f32_16x16x32_bf16 v[24:27], v[138:141], v[194:197], v[24:27]
	v_mfma_f32_16x16x32_bf16 v[12:15], v[114:117], v[202:205], v[12:15]
	v_mfma_f32_16x16x32_bf16 v[8:11], v[138:141], v[202:205], v[8:11]
	v_mfma_f32_16x16x32_bf16 v[60:63], v[118:121], v[176:179], v[60:63]
	v_mfma_f32_16x16x32_bf16 v[56:59], v[142:145], v[176:179], v[56:59]
	v_mfma_f32_16x16x32_bf16 v[44:47], v[118:121], v[190:193], v[44:47]
	v_mfma_f32_16x16x32_bf16 v[40:43], v[142:145], v[190:193], v[40:43]
	v_mfma_f32_16x16x32_bf16 v[28:31], v[118:121], v[198:201], v[28:31]
	v_mfma_f32_16x16x32_bf16 v[24:27], v[142:145], v[198:201], v[24:27]
	v_mfma_f32_16x16x32_bf16 v[12:15], v[118:121], v[212:215], v[12:15]
	v_mfma_f32_16x16x32_bf16 v[8:11], v[142:145], v[212:215], v[8:11]
	v_mfma_f32_16x16x32_bf16 v[52:55], v[146:149], v[172:175], v[52:55]
	v_mfma_f32_16x16x32_bf16 v[48:51], v[154:157], v[172:175], v[48:51]
	v_mfma_f32_16x16x32_bf16 v[36:39], v[146:149], v[180:183], v[36:39]
	v_mfma_f32_16x16x32_bf16 v[32:35], v[154:157], v[180:183], v[32:35]
	v_mfma_f32_16x16x32_bf16 v[20:23], v[146:149], v[194:197], v[20:23]
	v_mfma_f32_16x16x32_bf16 v[16:19], v[154:157], v[194:197], v[16:19]
	v_mfma_f32_16x16x32_bf16 v[4:7], v[146:149], v[202:205], v[4:7]
	v_mfma_f32_16x16x32_bf16 v[0:3], v[154:157], v[202:205], v[0:3]
	v_mfma_f32_16x16x32_bf16 v[52:55], v[150:153], v[176:179], v[52:55]
	v_mfma_f32_16x16x32_bf16 v[48:51], v[158:161], v[176:179], v[48:51]
	v_mfma_f32_16x16x32_bf16 v[36:39], v[150:153], v[190:193], v[36:39]
	v_mfma_f32_16x16x32_bf16 v[32:35], v[158:161], v[190:193], v[32:35]
	v_mfma_f32_16x16x32_bf16 v[20:23], v[150:153], v[198:201], v[20:23]
	v_mfma_f32_16x16x32_bf16 v[16:19], v[158:161], v[198:201], v[16:19]
	v_mfma_f32_16x16x32_bf16 v[4:7], v[150:153], v[212:215], v[4:7]
	v_mfma_f32_16x16x32_bf16 v[0:3], v[158:161], v[212:215], v[0:3]
	s_setprio 0
	s_barrier
	s_add_i32 s78, s78, 2
	s_add_u32 s40, s40, 0x100
	s_addc_u32 s41, s41, 0
	s_add_u32 s61, s61, 0x100
	s_addc_u32 s77, s77, 0
	s_cmp_gt_u32 s78, 13
	s_cbranch_scc0 .LBB0_1432
	s_and_b64 vcc, exec, s[54:55]
	s_cbranch_vccz .LBB0_1435
	s_barrier

; #define PG8_STAGE(bufoff, gbase, voff) do { _Pragma("unroll") for (int _i = 0; _i < 2; ++_i) \
;         __builtin_amdgcn_global_load_lds((const unsigned*)((const char*)(gbase) + (voff)[_i]), (PG8_LAS unsigned*)(lds + (bufoff) + ldsw + _i * 8192), 16, 0, 0); } while (0)
; #define PG8_LDA(dst, b, h) do { _Pragma("unroll") for (int m = 0; m < 4; ++m) _Pragma("unroll") for (int k = 0; k < 2; ++k) dst[m][k] = *(const PG8_LAS bf16x8*)(lds + PG8_SA(b, h) + aoff + m * 2048 + k * 1024); } while (0)
; #define PG8_LDB(dst, b, h) do { _Pragma("unroll") for (int n = 0; n < 2; ++n) _Pragma("unroll") for (int k = 0; k < 2; ++k) dst[n][k] = *(const PG8_LAS bf16x8*)(lds + PG8_SB(b, h) + boff + n * 2048 + k * 1024); } while (0)
; #define PG8_WAIT_V(n) asm volatile("s_waitcnt vmcnt(" #n ")" ::: "memory")
; #define PG8_WAIT_L(n) asm volatile("s_waitcnt lgkmcnt(" #n ")" ::: "memory")
; #define PG8_BAR __builtin_amdgcn_s_barrier()
; #define PG8_SCHED __builtin_amdgcn_sched_barrier(0)
; template <class Epi, class Sched, bool ALIGN_EPI = false, bool SP2 = false>
; __device__ __forceinline__ void gemm_phase(PG8_LAS unsigned char* lds, const Gemm g, const Sched& S, const Epi& E, int tid_in) {
;     ...
;             const bool last = (t == nt - 2);
;             const char* a1 = cA + (size_t)(t + 1) * kstep;
;             const char* a2 = last ? nA : cA + (size_t)(t + 2) * kstep; const char* b2 = last ? nB : cB + (size_t)(t + 2) * kstep;
;             const char* a3 = a2 + kstep; const char* b3 = b2 + kstep;
;             if (last && has_next) S.a_ready(nxt);
;             if constexpr (SP2) {
;             PG8_LDB(B0, 0, 0); PG8_LDB(B1, 0, 1); PG8_SCHED; PG8_LDA(At, 0, 0); PG8_STAGE(PG8_SA(1, 1), a1 + hstep, voffA);
;             PG8_WAIT_V(8); PG8_WAIT_L(0); PG8_BAR; PG8_MMA(0, 0, At, B0); PG8_MMA(0, 1, At, B1); PG8_BAR; PG8_SCHED;
;             PG8_LDA(At, 0, 1); PG8_STAGE(PG8_SB(0, 0), b2, voffB); PG8_STAGE(PG8_SB(0, 1), b2 + hstep, voffB); PG8_STAGE(PG8_SA(0, 0), a2, voffA);
;             PG8_WAIT_V(8); PG8_WAIT_L(0); PG8_BAR; PG8_MMA(1, 0, At, B0); PG8_MMA(1, 1, At, B1); PG8_BAR; PG8_SCHED;
;             PG8_LDB(B0, 1, 0); PG8_LDB(B1, 1, 1); PG8_SCHED; PG8_LDA(At, 1, 0); PG8_STAGE(PG8_SA(0, 1), a2 + hstep, voffA);
;             PG8_WAIT_V(8); PG8_WAIT_L(0); PG8_BAR; PG8_MMA(0, 0, At, B0); PG8_MMA(0, 1, At, B1); PG8_BAR; PG8_SCHED;
.LBB0_1601:
	s_add_u32 s54, s52, 0xfffc0080
	s_addc_u32 s55, s53, -1
	s_add_i32 s72, 0, 0x10000
	s_cmp_eq_u32 s71, 12
	s_cselect_b32 s57, s0, s55
	s_cselect_b32 s56, s1, s54
	s_cselect_b32 s55, s43, s70
	s_cselect_b32 s54, s47, s69
	s_add_i32 s74, 0, 0x14000
	v_add_u32_e32 v76, s72, v182
	v_add_u32_e32 v94, s74, v182
	ds_read_b128 v[60:63], v76
	ds_read_b128 v[64:67], v76 offset:1024
	ds_read_b128 v[72:75], v76 offset:2048
	ds_read_b128 v[76:79], v76 offset:3072
	ds_read_b128 v[82:85], v94
	ds_read_b128 v[86:89], v94 offset:1024
	ds_read_b128 v[90:93], v94 offset:2048
	ds_read_b128 v[94:97], v94 offset:3072
	v_lshl_add_u64 v[208:209], s[52:53], 0, v[172:173]
	s_add_i32 m0, s18, 0xc000
	ds_read_b128 v[162:165], v183
	ds_read_b128 v[176:179], v183 offset:1024
	ds_read_b128 v[184:187], v183 offset:2048
	ds_read_b128 v[188:191], v183 offset:3072
	ds_read_b128 v[192:195], v183 offset:4096
	ds_read_b128 v[196:199], v183 offset:5120
	ds_read_b128 v[200:203], v183 offset:6144
	ds_read_b128 v[204:207], v183 offset:7168
	global_load_lds_dwordx4 v[208:209], off
	v_lshl_add_u64 v[208:209], s[52:53], 0, v[174:175]
	s_add_i32 m0, s18, 0xe000
	s_nop 0
	global_load_lds_dwordx4 v[208:209], off
	s_waitcnt vmcnt(8) lgkmcnt(0)
	s_barrier
	s_setprio 1
	v_mfma_f32_16x16x32_bf16 v[158:161], v[60:63], v[162:165], v[158:161]
	v_mfma_f32_16x16x32_bf16 v[154:157], v[72:75], v[162:165], v[154:157]
	v_mfma_f32_16x16x32_bf16 v[142:145], v[60:63], v[184:187], v[142:145]
	v_mfma_f32_16x16x32_bf16 v[138:141], v[72:75], v[184:187], v[138:141]
	v_mfma_f32_16x16x32_bf16 v[126:129], v[60:63], v[192:195], v[126:129]
	v_mfma_f32_16x16x32_bf16 v[122:125], v[72:75], v[192:195], v[122:125]
	v_mfma_f32_16x16x32_bf16 v[110:113], v[60:63], v[200:203], v[110:113]
	v_mfma_f32_16x16x32_bf16 v[106:109], v[72:75], v[200:203], v[106:109]
	v_mfma_f32_16x16x32_bf16 v[158:161], v[64:67], v[176:179], v[158:161]
	v_mfma_f32_16x16x32_bf16 v[154:157], v[76:79], v[176:179], v[154:157]
	v_mfma_f32_16x16x32_bf16 v[142:145], v[64:67], v[188:191], v[142:145]
	v_mfma_f32_16x16x32_bf16 v[138:141], v[76:79], v[188:191], v[138:141]
	v_mfma_f32_16x16x32_bf16 v[126:129], v[64:67], v[196:199], v[126:129]
	v_mfma_f32_16x16x32_bf16 v[122:125], v[76:79], v[196:199], v[122:125]
	v_mfma_f32_16x16x32_bf16 v[110:113], v[64:67], v[204:207], v[110:113]
	v_mfma_f32_16x16x32_bf16 v[106:109], v[76:79], v[204:207], v[106:109]
	v_mfma_f32_16x16x32_bf16 v[150:153], v[82:85], v[162:165], v[150:153]
	v_mfma_f32_16x16x32_bf16 v[146:149], v[90:93], v[162:165], v[146:149]
	v_mfma_f32_16x16x32_bf16 v[134:137], v[82:85], v[184:187], v[134:137]
	v_mfma_f32_16x16x32_bf16 v[130:133], v[90:93], v[184:187], v[130:133]
	v_mfma_f32_16x16x32_bf16 v[118:121], v[82:85], v[192:195], v[118:121]
	v_mfma_f32_16x16x32_bf16 v[114:117], v[90:93], v[192:195], v[114:117]
	v_mfma_f32_16x16x32_bf16 v[102:105], v[82:85], v[200:203], v[102:105]
	v_mfma_f32_16x16x32_bf16 v[98:101], v[90:93], v[200:203], v[98:101]
	v_mfma_f32_16x16x32_bf16 v[150:153], v[86:89], v[176:179], v[150:153]
	v_mfma_f32_16x16x32_bf16 v[146:149], v[94:97], v[176:179], v[146:149]
	v_mfma_f32_16x16x32_bf16 v[134:137], v[86:89], v[188:191], v[134:137]
	v_mfma_f32_16x16x32_bf16 v[130:133], v[94:97], v[188:191], v[130:133]
	v_mfma_f32_16x16x32_bf16 v[118:121], v[86:89], v[196:199], v[118:121]
	v_mfma_f32_16x16x32_bf16 v[114:117], v[94:97], v[196:199], v[114:117]
	v_mfma_f32_16x16x32_bf16 v[102:105], v[86:89], v[204:207], v[102:105]
	v_mfma_f32_16x16x32_bf16 v[98:101], v[94:97], v[204:207], v[98:101]
	s_setprio 0
	s_barrier
	s_add_i32 s72, s72, s17
	v_lshl_add_u64 v[208:209], s[54:55], 0, v[80:81]
	s_mov_b32 m0, s72
	ds_read_b128 v[162:165], v183 offset:16384
	ds_read_b128 v[176:179], v183 offset:17408
	ds_read_b128 v[184:187], v183 offset:18432
	ds_read_b128 v[188:191], v183 offset:19456
	ds_read_b128 v[192:195], v183 offset:20480
	ds_read_b128 v[196:199], v183 offset:21504
	ds_read_b128 v[200:203], v183 offset:22528
	ds_read_b128 v[204:207], v183 offset:23552
	global_load_lds_dwordx4 v[208:209], off
	s_add_i32 m0, s72, 0x2000
	s_add_u32 s72, s54, 0x40000
	v_lshl_add_u64 v[210:211], s[54:55], 0, v[170:171]
	s_addc_u32 s73, s55, 0
	s_add_i32 s74, s74, s17
	global_load_lds_dwordx4 v[210:211], off
	v_lshl_add_u64 v[212:213], s[72:73], 0, v[80:81]
	s_mov_b32 m0, s74
	v_lshl_add_u64 v[214:215], s[56:57], 0, v[168:169]
	global_load_lds_dwordx4 v[212:213], off
	v_lshl_add_u64 v[212:213], s[72:73], 0, v[170:171]
	s_add_i32 m0, s74, 0x2000
	s_nop 0
	global_load_lds_dwordx4 v[212:213], off
	v_lshl_add_u64 v[212:213], s[56:57], 0, v[166:167]
	s_mov_b32 m0, s18
	s_nop 0
	global_load_lds_dwordx4 v[212:213], off
	s_mov_b32 m0, s19
	s_nop 0
	global_load_lds_dwordx4 v[214:215], off
	s_waitcnt vmcnt(8) lgkmcnt(0)
	s_barrier
; #define PG8_STAGE(bufoff, gbase, voff) do { _Pragma("unroll") for (int _i = 0; _i < 2; ++_i) \
;         __builtin_amdgcn_global_load_lds((const unsigned*)((const char*)(gbase) + (voff)[_i]), (PG8_LAS unsigned*)(lds + (bufoff) + ldsw + _i * 8192), 16, 0, 0); } while (0)
; #define PG8_LDA(dst, b, h) do { _Pragma("unroll") for (int m = 0; m < 4; ++m) _Pragma("unroll") for (int k = 0; k < 2; ++k) dst[m][k] = *(const PG8_LAS bf16x8*)(lds + PG8_SA(b, h) + aoff + m * 2048 + k * 1024); } while (0)
; #define PG8_LDB(dst, b, h) do { _Pragma("unroll") for (int n = 0; n < 2; ++n) _Pragma("unroll") for (int k = 0; k < 2; ++k) dst[n][k] = *(const PG8_LAS bf16x8*)(lds + PG8_SB(b, h) + boff + n * 2048 + k * 1024); } while (0)
; #define PG8_MMA(ai, bj, At, Bt) do { __builtin_amdgcn_s_setprio(1); _Pragma("unroll") for (int m = 0; m < 4; ++m) _Pragma("unroll") for (int n = 0; n < 2; ++n) _Pragma("unroll") for (int k = 0; k < 2; ++k) \
;         acc[ai][bj][m][n] = __builtin_amdgcn_mfma_f32_16x16x32_bf16(Bt[n][k], At[m][k], acc[ai][bj][m][n], 0, 0, 0); __builtin_amdgcn_s_setprio(0); } while (0)
; #define PG8_WAIT_V(n) asm volatile("s_waitcnt vmcnt(" #n ")" ::: "memory")
; #define PG8_WAIT_L(n) asm volatile("s_waitcnt lgkmcnt(" #n ")" ::: "memory")
; #define PG8_BAR __builtin_amdgcn_s_barrier()
; #define PG8_SCHED __builtin_amdgcn_sched_barrier(0)
; template <class Epi, class Sched, bool ALIGN_EPI = false, bool SP2 = false>
; __device__ __forceinline__ void gemm_phase(PG8_LAS unsigned char* lds, const Gemm g, const Sched& S, const Epi& E, int tid_in) {
;     ...
;             PG8_WAIT_V(8); PG8_WAIT_L(0); PG8_BAR; PG8_MMA(1, 0, At, B0); PG8_MMA(1, 1, At, B1); PG8_BAR; PG8_SCHED;
;             PG8_LDB(B0, 1, 0); PG8_LDB(B1, 1, 1); PG8_SCHED; PG8_LDA(At, 1, 0); PG8_STAGE(PG8_SA(0, 1), a2 + hstep, voffA);
;             PG8_WAIT_V(8); PG8_WAIT_L(0); PG8_BAR; PG8_MMA(0, 0, At, B0); PG8_MMA(0, 1, At, B1); PG8_BAR; PG8_SCHED;
	s_setprio 1
	v_mfma_f32_16x16x32_bf16 v[68:71], v[60:63], v[162:165], v[68:71]
	v_mfma_f32_16x16x32_bf16 v[56:59], v[72:75], v[162:165], v[56:59]
	v_mfma_f32_16x16x32_bf16 v[44:47], v[60:63], v[184:187], v[44:47]
	v_mfma_f32_16x16x32_bf16 v[40:43], v[72:75], v[184:187], v[40:43]
	v_mfma_f32_16x16x32_bf16 v[28:31], v[60:63], v[192:195], v[28:31]
	v_mfma_f32_16x16x32_bf16 v[24:27], v[72:75], v[192:195], v[24:27]
	v_mfma_f32_16x16x32_bf16 v[12:15], v[60:63], v[200:203], v[12:15]
	v_mfma_f32_16x16x32_bf16 v[8:11], v[72:75], v[200:203], v[8:11]
	v_mfma_f32_16x16x32_bf16 v[68:71], v[64:67], v[176:179], v[68:71]
	v_mfma_f32_16x16x32_bf16 v[56:59], v[76:79], v[176:179], v[56:59]
	v_mfma_f32_16x16x32_bf16 v[44:47], v[64:67], v[188:191], v[44:47]
	v_mfma_f32_16x16x32_bf16 v[40:43], v[76:79], v[188:191], v[40:43]
	v_mfma_f32_16x16x32_bf16 v[28:31], v[64:67], v[196:199], v[28:31]
	v_mfma_f32_16x16x32_bf16 v[24:27], v[76:79], v[196:199], v[24:27]
	v_mfma_f32_16x16x32_bf16 v[12:15], v[64:67], v[204:207], v[12:15]
	v_mfma_f32_16x16x32_bf16 v[8:11], v[76:79], v[204:207], v[8:11]
	v_mfma_f32_16x16x32_bf16 v[52:55], v[82:85], v[162:165], v[52:55]
	v_mfma_f32_16x16x32_bf16 v[48:51], v[90:93], v[162:165], v[48:51]
	v_mfma_f32_16x16x32_bf16 v[36:39], v[82:85], v[184:187], v[36:39]
	v_mfma_f32_16x16x32_bf16 v[32:35], v[90:93], v[184:187], v[32:35]
	v_mfma_f32_16x16x32_bf16 v[20:23], v[82:85], v[192:195], v[20:23]
	v_mfma_f32_16x16x32_bf16 v[16:19], v[90:93], v[192:195], v[16:19]
	v_mfma_f32_16x16x32_bf16 v[4:7], v[82:85], v[200:203], v[4:7]
	v_mfma_f32_16x16x32_bf16 v[0:3], v[90:93], v[200:203], v[0:3]
	v_mfma_f32_16x16x32_bf16 v[52:55], v[86:89], v[176:179], v[52:55]
	v_mfma_f32_16x16x32_bf16 v[48:51], v[94:97], v[176:179], v[48:51]
	v_mfma_f32_16x16x32_bf16 v[36:39], v[86:89], v[188:191], v[36:39]
	v_mfma_f32_16x16x32_bf16 v[32:35], v[94:97], v[188:191], v[32:35]
	v_mfma_f32_16x16x32_bf16 v[20:23], v[86:89], v[196:199], v[20:23]
	v_mfma_f32_16x16x32_bf16 v[16:19], v[94:97], v[196:199], v[16:19]
	v_mfma_f32_16x16x32_bf16 v[4:7], v[86:89], v[204:207], v[4:7]
	v_mfma_f32_16x16x32_bf16 v[0:3], v[94:97], v[204:207], v[0:3]
	s_setprio 0
	s_barrier
	s_add_i32 s72, 0, 0x18000
	s_add_i32 s73, 0, 0x1c000
	v_add_u32_e32 v76, s72, v182
	v_add_u32_e32 v94, s73, v182
	ds_read_b128 v[60:63], v76
	ds_read_b128 v[64:67], v76 offset:1024
	ds_read_b128 v[72:75], v76 offset:2048
	ds_read_b128 v[76:79], v76 offset:3072
	ds_read_b128 v[82:85], v94
	ds_read_b128 v[86:89], v94 offset:1024
	ds_read_b128 v[90:93], v94 offset:2048
	ds_read_b128 v[94:97], v94 offset:3072
	s_add_u32 s56, s56, 0x40000
	s_addc_u32 s57, s57, 0
	s_mov_b32 m0, s58
	v_lshl_add_u64 v[226:227], s[56:57], 0, v[166:167]
	ds_read_b128 v[162:165], v183 offset:32768
	ds_read_b128 v[176:179], v183 offset:33792
	ds_read_b128 v[184:187], v183 offset:34816
	ds_read_b128 v[188:191], v183 offset:35840
	ds_read_b128 v[192:195], v183 offset:36864
	ds_read_b128 v[196:199], v183 offset:37888
	ds_read_b128 v[200:203], v183 offset:38912
	ds_read_b128 v[204:207], v183 offset:39936
	global_load_lds_dwordx4 v[226:227], off
	v_lshl_add_u64 v[226:227], s[56:57], 0, v[168:169]
	s_mov_b32 m0, s59
	s_nop 0
	global_load_lds_dwordx4 v[226:227], off
	s_waitcnt vmcnt(8) lgkmcnt(0)
	s_barrier
	s_setprio 1
	v_mfma_f32_16x16x32_bf16 v[158:161], v[60:63], v[162:165], v[158:161]
	v_mfma_f32_16x16x32_bf16 v[154:157], v[72:75], v[162:165], v[154:157]
	v_mfma_f32_16x16x32_bf16 v[142:145], v[60:63], v[184:187], v[142:145]
	v_mfma_f32_16x16x32_bf16 v[138:141], v[72:75], v[184:187], v[138:141]
	v_mfma_f32_16x16x32_bf16 v[126:129], v[60:63], v[192:195], v[126:129]
	v_mfma_f32_16x16x32_bf16 v[122:125], v[72:75], v[192:195], v[122:125]
	v_mfma_f32_16x16x32_bf16 v[110:113], v[60:63], v[200:203], v[110:113]
	v_mfma_f32_16x16x32_bf16 v[106:109], v[72:75], v[200:203], v[106:109]
	v_mfma_f32_16x16x32_bf16 v[158:161], v[64:67], v[176:179], v[158:161]
	v_mfma_f32_16x16x32_bf16 v[154:157], v[76:79], v[176:179], v[154:157]
	v_mfma_f32_16x16x32_bf16 v[142:145], v[64:67], v[188:191], v[142:145]
	v_mfma_f32_16x16x32_bf16 v[138:141], v[76:79], v[188:191], v[138:141]
	v_mfma_f32_16x16x32_bf16 v[126:129], v[64:67], v[196:199], v[126:129]
	v_mfma_f32_16x16x32_bf16 v[122:125], v[76:79], v[196:199], v[122:125]
	v_mfma_f32_16x16x32_bf16 v[110:113], v[64:67], v[204:207], v[110:113]
	v_mfma_f32_16x16x32_bf16 v[106:109], v[76:79], v[204:207], v[106:109]
	v_mfma_f32_16x16x32_bf16 v[150:153], v[82:85], v[162:165], v[150:153]
	v_mfma_f32_16x16x32_bf16 v[146:149], v[90:93], v[162:165], v[146:149]
	v_mfma_f32_16x16x32_bf16 v[134:137], v[82:85], v[184:187], v[134:137]
	v_mfma_f32_16x16x32_bf16 v[130:133], v[90:93], v[184:187], v[130:133]
	v_mfma_f32_16x16x32_bf16 v[118:121], v[82:85], v[192:195], v[118:121]
	v_mfma_f32_16x16x32_bf16 v[114:117], v[90:93], v[192:195], v[114:117]
	v_mfma_f32_16x16x32_bf16 v[102:105], v[82:85], v[200:203], v[102:105]
	v_mfma_f32_16x16x32_bf16 v[98:101], v[90:93], v[200:203], v[98:101]
	v_mfma_f32_16x16x32_bf16 v[150:153], v[86:89], v[176:179], v[150:153]
	v_mfma_f32_16x16x32_bf16 v[146:149], v[94:97], v[176:179], v[146:149]
	v_mfma_f32_16x16x32_bf16 v[134:137], v[86:89], v[188:191], v[134:137]
	v_mfma_f32_16x16x32_bf16 v[130:133], v[94:97], v[188:191], v[130:133]
	v_mfma_f32_16x16x32_bf16 v[118:121], v[86:89], v[196:199], v[118:121]
	v_mfma_f32_16x16x32_bf16 v[114:117], v[94:97], v[196:199], v[114:117]
	v_mfma_f32_16x16x32_bf16 v[102:105], v[86:89], v[204:207], v[102:105]
	v_mfma_f32_16x16x32_bf16 v[98:101], v[94:97], v[204:207], v[98:101]
	s_setprio 0
	s_barrier
; #define PG8_STAGE(bufoff, gbase, voff) do { _Pragma("unroll") for (int _i = 0; _i < 2; ++_i) \
;         __builtin_amdgcn_global_load_lds((const unsigned*)((const char*)(gbase) + (voff)[_i]), (PG8_LAS unsigned*)(lds + (bufoff) + ldsw + _i * 8192), 16, 0, 0); } while (0)
; #define PG8_LDA(dst, b, h) do { _Pragma("unroll") for (int m = 0; m < 4; ++m) _Pragma("unroll") for (int k = 0; k < 2; ++k) dst[m][k] = *(const PG8_LAS bf16x8*)(lds + PG8_SA(b, h) + aoff + m * 2048 + k * 1024); } while (0)
; #define PG8_MMA(ai, bj, At, Bt) do { __builtin_amdgcn_s_setprio(1); _Pragma("unroll") for (int m = 0; m < 4; ++m) _Pragma("unroll") for (int n = 0; n < 2; ++n) _Pragma("unroll") for (int k = 0; k < 2; ++k) \
;         acc[ai][bj][m][n] = __builtin_amdgcn_mfma_f32_16x16x32_bf16(Bt[n][k], At[m][k], acc[ai][bj][m][n], 0, 0, 0); __builtin_amdgcn_s_setprio(0); } while (0)
; #define PG8_WAIT_V(n) asm volatile("s_waitcnt vmcnt(" #n ")" ::: "memory")
; #define PG8_WAIT_L(n) asm volatile("s_waitcnt lgkmcnt(" #n ")" ::: "memory")
; #define PG8_BAR __builtin_amdgcn_s_barrier()
; #define PG8_SCHED __builtin_amdgcn_sched_barrier(0)
; template <class Epi, class Sched, bool ALIGN_EPI = false, bool SP2 = false>
; __device__ __forceinline__ void gemm_phase(PG8_LAS unsigned char* lds, const Gemm g, const Sched& S, const Epi& E, int tid_in) {
;     ...
;             PG8_LDA(At, 1, 1); PG8_STAGE(PG8_SB(1, 0), b3, voffB); PG8_STAGE(PG8_SB(1, 1), b3 + hstep, voffB); PG8_STAGE(PG8_SA(1, 0), a3, voffA);
;             PG8_WAIT_V(8); PG8_WAIT_L(0); PG8_BAR; PG8_MMA(1, 0, At, B0); PG8_MMA(1, 1, At, B1); PG8_BAR; PG8_SCHED;
;     ...
;         if constexpr (ALIGN_EPI) { if (wr == 0) PG8_BAR; }
	s_add_i32 s56, s72, s17
	v_lshl_add_u64 v[208:209], v[208:209], 0, s[6:7]
	s_mov_b32 m0, s56
	ds_read_b128 v[162:165], v183 offset:49152
	ds_read_b128 v[176:179], v183 offset:50176
	ds_read_b128 v[184:187], v183 offset:51200
	ds_read_b128 v[188:191], v183 offset:52224
	ds_read_b128 v[192:195], v183 offset:53248
	ds_read_b128 v[196:199], v183 offset:54272
	ds_read_b128 v[200:203], v183 offset:55296
	ds_read_b128 v[204:207], v183 offset:56320
	global_load_lds_dwordx4 v[208:209], off
	s_add_i32 m0, s56, 0x2000
	s_add_u32 s54, s54, 0x40080
	v_lshl_add_u64 v[208:209], v[210:211], 0, s[6:7]
	s_addc_u32 s55, s55, 0
	s_add_i32 s56, s73, s17
	global_load_lds_dwordx4 v[208:209], off
	v_lshl_add_u64 v[208:209], s[54:55], 0, v[80:81]
	s_mov_b32 m0, s56
	s_nop 0
	global_load_lds_dwordx4 v[208:209], off
	v_lshl_add_u64 v[208:209], s[54:55], 0, v[170:171]
	s_add_i32 m0, s56, 0x2000
	s_nop 0
	global_load_lds_dwordx4 v[208:209], off
	v_lshl_add_u64 v[208:209], v[212:213], 0, s[6:7]
	s_mov_b32 m0, s62
	s_nop 0
	global_load_lds_dwordx4 v[208:209], off
	v_lshl_add_u64 v[208:209], v[214:215], 0, s[6:7]
	s_mov_b32 m0, s63
	s_nop 0
	global_load_lds_dwordx4 v[208:209], off
	s_waitcnt vmcnt(8) lgkmcnt(0)
	s_barrier
	s_setprio 1
	v_mfma_f32_16x16x32_bf16 v[68:71], v[60:63], v[162:165], v[68:71]
	v_mfma_f32_16x16x32_bf16 v[56:59], v[72:75], v[162:165], v[56:59]
	v_mfma_f32_16x16x32_bf16 v[44:47], v[60:63], v[184:187], v[44:47]
	v_mfma_f32_16x16x32_bf16 v[40:43], v[72:75], v[184:187], v[40:43]
	v_mfma_f32_16x16x32_bf16 v[28:31], v[60:63], v[192:195], v[28:31]
	v_mfma_f32_16x16x32_bf16 v[24:27], v[72:75], v[192:195], v[24:27]
	v_mfma_f32_16x16x32_bf16 v[12:15], v[60:63], v[200:203], v[12:15]
	v_mfma_f32_16x16x32_bf16 v[8:11], v[72:75], v[200:203], v[8:11]
	v_mfma_f32_16x16x32_bf16 v[68:71], v[64:67], v[176:179], v[68:71]
	v_mfma_f32_16x16x32_bf16 v[56:59], v[76:79], v[176:179], v[56:59]
	v_mfma_f32_16x16x32_bf16 v[44:47], v[64:67], v[188:191], v[44:47]
	v_mfma_f32_16x16x32_bf16 v[40:43], v[76:79], v[188:191], v[40:43]
	v_mfma_f32_16x16x32_bf16 v[28:31], v[64:67], v[196:199], v[28:31]
	v_mfma_f32_16x16x32_bf16 v[24:27], v[76:79], v[196:199], v[24:27]
	v_mfma_f32_16x16x32_bf16 v[12:15], v[64:67], v[204:207], v[12:15]
	v_mfma_f32_16x16x32_bf16 v[8:11], v[76:79], v[204:207], v[8:11]
	v_mfma_f32_16x16x32_bf16 v[52:55], v[82:85], v[162:165], v[52:55]
	v_mfma_f32_16x16x32_bf16 v[48:51], v[90:93], v[162:165], v[48:51]
	v_mfma_f32_16x16x32_bf16 v[36:39], v[82:85], v[184:187], v[36:39]
	v_mfma_f32_16x16x32_bf16 v[32:35], v[90:93], v[184:187], v[32:35]
	v_mfma_f32_16x16x32_bf16 v[20:23], v[82:85], v[192:195], v[20:23]
	v_mfma_f32_16x16x32_bf16 v[16:19], v[90:93], v[192:195], v[16:19]
	v_mfma_f32_16x16x32_bf16 v[4:7], v[82:85], v[200:203], v[4:7]
	v_mfma_f32_16x16x32_bf16 v[0:3], v[90:93], v[200:203], v[0:3]
	v_mfma_f32_16x16x32_bf16 v[52:55], v[86:89], v[176:179], v[52:55]
	v_mfma_f32_16x16x32_bf16 v[48:51], v[94:97], v[176:179], v[48:51]
	v_mfma_f32_16x16x32_bf16 v[36:39], v[86:89], v[188:191], v[36:39]
	v_mfma_f32_16x16x32_bf16 v[32:35], v[94:97], v[188:191], v[32:35]
	v_mfma_f32_16x16x32_bf16 v[20:23], v[86:89], v[196:199], v[20:23]
	v_mfma_f32_16x16x32_bf16 v[16:19], v[94:97], v[196:199], v[16:19]
	v_mfma_f32_16x16x32_bf16 v[4:7], v[86:89], v[204:207], v[4:7]
	v_mfma_f32_16x16x32_bf16 v[0:3], v[94:97], v[204:207], v[0:3]
	s_setprio 0
	s_barrier
	s_add_i32 s71, s71, 2
	s_add_u32 s52, s52, 0x100
	s_addc_u32 s53, s53, 0
	s_add_u32 s69, s69, 0x100
	s_addc_u32 s70, s70, 0
	s_cmp_gt_u32 s71, 13
	s_cbranch_scc0 .LBB0_1601
	s_and_b64 vcc, exec, s[40:41]
	s_cbranch_vccz .LBB0_1604
	s_barrier

; #define PG8_STAGE(bufoff, gbase, voff) do { _Pragma("unroll") for (int _i = 0; _i < 2; ++_i) \
;         __builtin_amdgcn_global_load_lds((const unsigned*)((const char*)(gbase) + (voff)[_i]), (PG8_LAS unsigned*)(lds + (bufoff) + ldsw + _i * 8192), 16, 0, 0); } while (0)
; #define PG8_LDA(dst, b, h) do { _Pragma("unroll") for (int m = 0; m < 4; ++m) _Pragma("unroll") for (int k = 0; k < 2; ++k) dst[m][k] = *(const PG8_LAS bf16x8*)(lds + PG8_SA(b, h) + aoff + m * 2048 + k * 1024); } while (0)
; #define PG8_LDB(dst, b, h) do { _Pragma("unroll") for (int n = 0; n < 2; ++n) _Pragma("unroll") for (int k = 0; k < 2; ++k) dst[n][k] = *(const PG8_LAS bf16x8*)(lds + PG8_SB(b, h) + boff + n * 2048 + k * 1024); } while (0)
; #define PG8_WAIT_V(n) asm volatile("s_waitcnt vmcnt(" #n ")" ::: "memory")
; #define PG8_WAIT_L(n) asm volatile("s_waitcnt lgkmcnt(" #n ")" ::: "memory")
; #define PG8_BAR __builtin_amdgcn_s_barrier()
; #define PG8_SCHED __builtin_amdgcn_sched_barrier(0)
; template <class Epi, class Sched, bool ALIGN_EPI = false, bool SP2 = false>
; __device__ __forceinline__ void gemm_phase(PG8_LAS unsigned char* lds, const Gemm g, const Sched& S, const Epi& E, int tid_in) {
;     ...
;             const bool last = (t == nt - 2);
;             const char* a1 = cA + (size_t)(t + 1) * kstep;
;             const char* a2 = last ? nA : cA + (size_t)(t + 2) * kstep; const char* b2 = last ? nB : cB + (size_t)(t + 2) * kstep;
;             const char* a3 = a2 + kstep; const char* b3 = b2 + kstep;
;             if (last && has_next) S.a_ready(nxt);
;             if constexpr (SP2) {
;             PG8_LDB(B0, 0, 0); PG8_LDB(B1, 0, 1); PG8_SCHED; PG8_LDA(At, 0, 0); PG8_STAGE(PG8_SA(1, 1), a1 + hstep, voffA);
;             PG8_WAIT_V(8); PG8_WAIT_L(0); PG8_BAR; PG8_MMA(0, 0, At, B0); PG8_MMA(0, 1, At, B1); PG8_BAR; PG8_SCHED;
;             PG8_LDA(At, 0, 1); PG8_STAGE(PG8_SB(0, 0), b2, voffB); PG8_STAGE(PG8_SB(0, 1), b2 + hstep, voffB); PG8_STAGE(PG8_SA(0, 0), a2, voffA);
;             PG8_WAIT_V(8); PG8_WAIT_L(0); PG8_BAR; PG8_MMA(1, 0, At, B0); PG8_MMA(1, 1, At, B1); PG8_BAR; PG8_SCHED;
;             PG8_LDB(B0, 1, 0); PG8_LDB(B1, 1, 1); PG8_SCHED; PG8_LDA(At, 1, 0); PG8_STAGE(PG8_SA(0, 1), a2 + hstep, voffA);
;             PG8_WAIT_V(8); PG8_WAIT_L(0); PG8_BAR; PG8_MMA(0, 0, At, B0); PG8_MMA(0, 1, At, B1); PG8_BAR; PG8_SCHED;
.LBB0_1689:
	s_add_u32 s4, s2, 0x100
	s_addc_u32 s5, s3, 0
	s_add_i32 s65, 0, 0x10000
	s_cmp_eq_u32 s43, 40
	s_cselect_b32 s41, s61, s5
	s_cselect_b32 s40, s60, s4
	s_cselect_b32 s9, s63, s1
	s_cselect_b32 s8, s62, s0
	s_add_i32 s77, 0, 0x14000
	v_add_u32_e32 v126, s65, v202
	v_add_u32_e32 v158, s77, v202
	ds_read_b128 v[90:93], v126
	ds_read_b128 v[102:105], v126 offset:1024
	ds_read_b128 v[114:117], v126 offset:2048
	ds_read_b128 v[126:129], v126 offset:3072
	ds_read_b128 v[138:141], v158
	ds_read_b128 v[150:153], v158 offset:1024
	ds_read_b128 v[154:157], v158 offset:2048
	ds_read_b128 v[158:161], v158 offset:3072
	v_lshl_add_u64 v[208:209], s[2:3], 0, v[168:169]
	s_add_i32 m0, s15, 0xc000
	ds_read_b128 v[172:175], v203
	ds_read_b128 v[176:179], v203 offset:1024
	ds_read_b128 v[180:183], v203 offset:2048
	ds_read_b128 v[184:187], v203 offset:3072
	ds_read_b128 v[188:191], v203 offset:4096
	ds_read_b128 v[192:195], v203 offset:5120
	ds_read_b128 v[196:199], v203 offset:6144
	ds_read_b128 v[204:207], v203 offset:7168
	global_load_lds_dwordx4 v[208:209], off
	v_lshl_add_u64 v[208:209], s[2:3], 0, v[170:171]
	s_add_i32 m0, s15, 0xe000
	s_nop 0
	global_load_lds_dwordx4 v[208:209], off
	s_waitcnt vmcnt(8) lgkmcnt(0)
	s_barrier
	s_setprio 1
	v_mfma_f32_16x16x32_bf16 v[146:149], v[90:93], v[172:175], v[146:149]
	v_mfma_f32_16x16x32_bf16 v[142:145], v[114:117], v[172:175], v[142:145]
	v_mfma_f32_16x16x32_bf16 v[122:125], v[90:93], v[180:183], v[122:125]
	v_mfma_f32_16x16x32_bf16 v[118:121], v[114:117], v[180:183], v[118:121]
	v_mfma_f32_16x16x32_bf16 v[98:101], v[90:93], v[188:191], v[98:101]
	v_mfma_f32_16x16x32_bf16 v[94:97], v[114:117], v[188:191], v[94:97]
	v_mfma_f32_16x16x32_bf16 v[76:79], v[90:93], v[196:199], v[76:79]
	v_mfma_f32_16x16x32_bf16 v[72:75], v[114:117], v[196:199], v[72:75]
	v_mfma_f32_16x16x32_bf16 v[146:149], v[102:105], v[176:179], v[146:149]
	v_mfma_f32_16x16x32_bf16 v[142:145], v[126:129], v[176:179], v[142:145]
	v_mfma_f32_16x16x32_bf16 v[122:125], v[102:105], v[184:187], v[122:125]
	v_mfma_f32_16x16x32_bf16 v[118:121], v[126:129], v[184:187], v[118:121]
	v_mfma_f32_16x16x32_bf16 v[98:101], v[102:105], v[192:195], v[98:101]
	v_mfma_f32_16x16x32_bf16 v[94:97], v[126:129], v[192:195], v[94:97]
	v_mfma_f32_16x16x32_bf16 v[76:79], v[102:105], v[204:207], v[76:79]
	v_mfma_f32_16x16x32_bf16 v[72:75], v[126:129], v[204:207], v[72:75]
	v_mfma_f32_16x16x32_bf16 v[134:137], v[138:141], v[172:175], v[134:137]
	v_mfma_f32_16x16x32_bf16 v[130:133], v[154:157], v[172:175], v[130:133]
	v_mfma_f32_16x16x32_bf16 v[110:113], v[138:141], v[180:183], v[110:113]
	v_mfma_f32_16x16x32_bf16 v[106:109], v[154:157], v[180:183], v[106:109]
	v_mfma_f32_16x16x32_bf16 v[86:89], v[138:141], v[188:191], v[86:89]
	v_mfma_f32_16x16x32_bf16 v[82:85], v[154:157], v[188:191], v[82:85]
	v_mfma_f32_16x16x32_bf16 v[68:71], v[138:141], v[196:199], v[68:71]
	v_mfma_f32_16x16x32_bf16 v[64:67], v[154:157], v[196:199], v[64:67]
	v_mfma_f32_16x16x32_bf16 v[134:137], v[150:153], v[176:179], v[134:137]
	v_mfma_f32_16x16x32_bf16 v[130:133], v[158:161], v[176:179], v[130:133]
	v_mfma_f32_16x16x32_bf16 v[110:113], v[150:153], v[184:187], v[110:113]
	v_mfma_f32_16x16x32_bf16 v[106:109], v[158:161], v[184:187], v[106:109]
	v_mfma_f32_16x16x32_bf16 v[86:89], v[150:153], v[192:195], v[86:89]
	v_mfma_f32_16x16x32_bf16 v[82:85], v[158:161], v[192:195], v[82:85]
	v_mfma_f32_16x16x32_bf16 v[68:71], v[150:153], v[204:207], v[68:71]
	v_mfma_f32_16x16x32_bf16 v[64:67], v[158:161], v[204:207], v[64:67]
	s_setprio 0
	s_barrier
	s_add_i32 s2, s65, s14
	v_lshl_add_u64 v[208:209], s[8:9], 0, v[80:81]
	s_mov_b32 m0, s2
	ds_read_b128 v[172:175], v203 offset:16384
	ds_read_b128 v[176:179], v203 offset:17408
	ds_read_b128 v[180:183], v203 offset:18432
	ds_read_b128 v[184:187], v203 offset:19456
	ds_read_b128 v[188:191], v203 offset:20480
	ds_read_b128 v[192:195], v203 offset:21504
	ds_read_b128 v[196:199], v203 offset:22528
	ds_read_b128 v[204:207], v203 offset:23552
	global_load_lds_dwordx4 v[208:209], off
	s_add_i32 m0, s2, 0x2000
	s_add_u32 s2, s8, 0xb0000
	v_lshl_add_u64 v[210:211], s[8:9], 0, v[166:167]
	s_addc_u32 s3, s9, 0
	s_add_i32 s65, s77, s14
	global_load_lds_dwordx4 v[210:211], off
	v_lshl_add_u64 v[212:213], s[2:3], 0, v[80:81]
	s_mov_b32 m0, s65
	v_lshl_add_u64 v[214:215], s[40:41], 0, v[164:165]
	global_load_lds_dwordx4 v[212:213], off
	v_lshl_add_u64 v[212:213], s[2:3], 0, v[166:167]
	s_add_i32 m0, s65, 0x2000
	s_nop 0
	global_load_lds_dwordx4 v[212:213], off
	v_lshl_add_u64 v[212:213], s[40:41], 0, v[162:163]
	s_mov_b32 m0, s15
	s_nop 0
	global_load_lds_dwordx4 v[212:213], off
	s_mov_b32 m0, s16
	s_nop 0
	global_load_lds_dwordx4 v[214:215], off
	s_waitcnt vmcnt(8) lgkmcnt(0)
	s_barrier
; #define PG8_STAGE(bufoff, gbase, voff) do { _Pragma("unroll") for (int _i = 0; _i < 2; ++_i) \
;         __builtin_amdgcn_global_load_lds((const unsigned*)((const char*)(gbase) + (voff)[_i]), (PG8_LAS unsigned*)(lds + (bufoff) + ldsw + _i * 8192), 16, 0, 0); } while (0)
; #define PG8_LDA(dst, b, h) do { _Pragma("unroll") for (int m = 0; m < 4; ++m) _Pragma("unroll") for (int k = 0; k < 2; ++k) dst[m][k] = *(const PG8_LAS bf16x8*)(lds + PG8_SA(b, h) + aoff + m * 2048 + k * 1024); } while (0)
; #define PG8_LDB(dst, b, h) do { _Pragma("unroll") for (int n = 0; n < 2; ++n) _Pragma("unroll") for (int k = 0; k < 2; ++k) dst[n][k] = *(const PG8_LAS bf16x8*)(lds + PG8_SB(b, h) + boff + n * 2048 + k * 1024); } while (0)
; #define PG8_MMA(ai, bj, At, Bt) do { __builtin_amdgcn_s_setprio(1); _Pragma("unroll") for (int m = 0; m < 4; ++m) _Pragma("unroll") for (int n = 0; n < 2; ++n) _Pragma("unroll") for (int k = 0; k < 2; ++k) \
;         acc[ai][bj][m][n] = __builtin_amdgcn_mfma_f32_16x16x32_bf16(Bt[n][k], At[m][k], acc[ai][bj][m][n], 0, 0, 0); __builtin_amdgcn_s_setprio(0); } while (0)
; #define PG8_WAIT_V(n) asm volatile("s_waitcnt vmcnt(" #n ")" ::: "memory")
; #define PG8_WAIT_L(n) asm volatile("s_waitcnt lgkmcnt(" #n ")" ::: "memory")
; #define PG8_BAR __builtin_amdgcn_s_barrier()
; #define PG8_SCHED __builtin_amdgcn_sched_barrier(0)
; template <class Epi, class Sched, bool ALIGN_EPI = false, bool SP2 = false>
; __device__ __forceinline__ void gemm_phase(PG8_LAS unsigned char* lds, const Gemm g, const Sched& S, const Epi& E, int tid_in) {
;     ...
;             PG8_WAIT_V(8); PG8_WAIT_L(0); PG8_BAR; PG8_MMA(1, 0, At, B0); PG8_MMA(1, 1, At, B1); PG8_BAR; PG8_SCHED;
;             PG8_LDB(B0, 1, 0); PG8_LDB(B1, 1, 1); PG8_SCHED; PG8_LDA(At, 1, 0); PG8_STAGE(PG8_SA(0, 1), a2 + hstep, voffA);
;             PG8_WAIT_V(8); PG8_WAIT_L(0); PG8_BAR; PG8_MMA(0, 0, At, B0); PG8_MMA(0, 1, At, B1); PG8_BAR; PG8_SCHED;
	s_setprio 1
	v_mfma_f32_16x16x32_bf16 v[60:63], v[90:93], v[172:175], v[60:63]
	v_mfma_f32_16x16x32_bf16 v[56:59], v[114:117], v[172:175], v[56:59]
	v_mfma_f32_16x16x32_bf16 v[44:47], v[90:93], v[180:183], v[44:47]
	v_mfma_f32_16x16x32_bf16 v[40:43], v[114:117], v[180:183], v[40:43]
	v_mfma_f32_16x16x32_bf16 v[28:31], v[90:93], v[188:191], v[28:31]
	v_mfma_f32_16x16x32_bf16 v[24:27], v[114:117], v[188:191], v[24:27]
	v_mfma_f32_16x16x32_bf16 v[12:15], v[90:93], v[196:199], v[12:15]
	v_mfma_f32_16x16x32_bf16 v[8:11], v[114:117], v[196:199], v[8:11]
	v_mfma_f32_16x16x32_bf16 v[60:63], v[102:105], v[176:179], v[60:63]
	v_mfma_f32_16x16x32_bf16 v[56:59], v[126:129], v[176:179], v[56:59]
	v_mfma_f32_16x16x32_bf16 v[44:47], v[102:105], v[184:187], v[44:47]
	v_mfma_f32_16x16x32_bf16 v[40:43], v[126:129], v[184:187], v[40:43]
	v_mfma_f32_16x16x32_bf16 v[28:31], v[102:105], v[192:195], v[28:31]
	v_mfma_f32_16x16x32_bf16 v[24:27], v[126:129], v[192:195], v[24:27]
	v_mfma_f32_16x16x32_bf16 v[12:15], v[102:105], v[204:207], v[12:15]
	v_mfma_f32_16x16x32_bf16 v[8:11], v[126:129], v[204:207], v[8:11]
	v_mfma_f32_16x16x32_bf16 v[52:55], v[138:141], v[172:175], v[52:55]
	v_mfma_f32_16x16x32_bf16 v[48:51], v[154:157], v[172:175], v[48:51]
	v_mfma_f32_16x16x32_bf16 v[36:39], v[138:141], v[180:183], v[36:39]
	v_mfma_f32_16x16x32_bf16 v[32:35], v[154:157], v[180:183], v[32:35]
	v_mfma_f32_16x16x32_bf16 v[20:23], v[138:141], v[188:191], v[20:23]
	v_mfma_f32_16x16x32_bf16 v[16:19], v[154:157], v[188:191], v[16:19]
	v_mfma_f32_16x16x32_bf16 v[4:7], v[138:141], v[196:199], v[4:7]
	v_mfma_f32_16x16x32_bf16 v[0:3], v[154:157], v[196:199], v[0:3]
	v_mfma_f32_16x16x32_bf16 v[52:55], v[150:153], v[176:179], v[52:55]
	v_mfma_f32_16x16x32_bf16 v[48:51], v[158:161], v[176:179], v[48:51]
	v_mfma_f32_16x16x32_bf16 v[36:39], v[150:153], v[184:187], v[36:39]
	v_mfma_f32_16x16x32_bf16 v[32:35], v[158:161], v[184:187], v[32:35]
	v_mfma_f32_16x16x32_bf16 v[20:23], v[150:153], v[192:195], v[20:23]
	v_mfma_f32_16x16x32_bf16 v[16:19], v[158:161], v[192:195], v[16:19]
	v_mfma_f32_16x16x32_bf16 v[4:7], v[150:153], v[204:207], v[4:7]
	v_mfma_f32_16x16x32_bf16 v[0:3], v[158:161], v[204:207], v[0:3]
	s_setprio 0
	s_barrier
	s_add_i32 s65, 0, 0x18000
	s_add_i32 s77, 0, 0x1c000
	v_add_u32_e32 v126, s65, v202
	v_add_u32_e32 v158, s77, v202
	ds_read_b128 v[90:93], v126
	ds_read_b128 v[102:105], v126 offset:1024
	ds_read_b128 v[114:117], v126 offset:2048
	ds_read_b128 v[126:129], v126 offset:3072
	ds_read_b128 v[138:141], v158
	ds_read_b128 v[150:153], v158 offset:1024
	ds_read_b128 v[154:157], v158 offset:2048
	ds_read_b128 v[158:161], v158 offset:3072
	s_add_u32 s2, s40, 0xb0000
	s_addc_u32 s3, s41, 0
	s_mov_b32 m0, s17
	v_lshl_add_u64 v[226:227], s[2:3], 0, v[162:163]
	ds_read_b128 v[172:175], v203 offset:32768
	ds_read_b128 v[176:179], v203 offset:33792
	ds_read_b128 v[180:183], v203 offset:34816
	ds_read_b128 v[184:187], v203 offset:35840
	ds_read_b128 v[188:191], v203 offset:36864
	ds_read_b128 v[192:195], v203 offset:37888
	ds_read_b128 v[196:199], v203 offset:38912
	ds_read_b128 v[204:207], v203 offset:39936
	global_load_lds_dwordx4 v[226:227], off
	v_lshl_add_u64 v[226:227], s[2:3], 0, v[164:165]
	s_mov_b32 m0, s18
	s_nop 0
	global_load_lds_dwordx4 v[226:227], off
	s_waitcnt vmcnt(8) lgkmcnt(0)
	s_barrier
	s_setprio 1
	v_mfma_f32_16x16x32_bf16 v[146:149], v[90:93], v[172:175], v[146:149]
	v_mfma_f32_16x16x32_bf16 v[142:145], v[114:117], v[172:175], v[142:145]
	v_mfma_f32_16x16x32_bf16 v[122:125], v[90:93], v[180:183], v[122:125]
	v_mfma_f32_16x16x32_bf16 v[118:121], v[114:117], v[180:183], v[118:121]
	v_mfma_f32_16x16x32_bf16 v[98:101], v[90:93], v[188:191], v[98:101]
	v_mfma_f32_16x16x32_bf16 v[94:97], v[114:117], v[188:191], v[94:97]
	v_mfma_f32_16x16x32_bf16 v[76:79], v[90:93], v[196:199], v[76:79]
	v_mfma_f32_16x16x32_bf16 v[72:75], v[114:117], v[196:199], v[72:75]
	v_mfma_f32_16x16x32_bf16 v[146:149], v[102:105], v[176:179], v[146:149]
	v_mfma_f32_16x16x32_bf16 v[142:145], v[126:129], v[176:179], v[142:145]
	v_mfma_f32_16x16x32_bf16 v[122:125], v[102:105], v[184:187], v[122:125]
	v_mfma_f32_16x16x32_bf16 v[118:121], v[126:129], v[184:187], v[118:121]
	v_mfma_f32_16x16x32_bf16 v[98:101], v[102:105], v[192:195], v[98:101]
	v_mfma_f32_16x16x32_bf16 v[94:97], v[126:129], v[192:195], v[94:97]
	v_mfma_f32_16x16x32_bf16 v[76:79], v[102:105], v[204:207], v[76:79]
	v_mfma_f32_16x16x32_bf16 v[72:75], v[126:129], v[204:207], v[72:75]
	v_mfma_f32_16x16x32_bf16 v[134:137], v[138:141], v[172:175], v[134:137]
	v_mfma_f32_16x16x32_bf16 v[130:133], v[154:157], v[172:175], v[130:133]
	v_mfma_f32_16x16x32_bf16 v[110:113], v[138:141], v[180:183], v[110:113]
	v_mfma_f32_16x16x32_bf16 v[106:109], v[154:157], v[180:183], v[106:109]
	v_mfma_f32_16x16x32_bf16 v[86:89], v[138:141], v[188:191], v[86:89]
	v_mfma_f32_16x16x32_bf16 v[82:85], v[154:157], v[188:191], v[82:85]
	v_mfma_f32_16x16x32_bf16 v[68:71], v[138:141], v[196:199], v[68:71]
	v_mfma_f32_16x16x32_bf16 v[64:67], v[154:157], v[196:199], v[64:67]
	v_mfma_f32_16x16x32_bf16 v[134:137], v[150:153], v[176:179], v[134:137]
	v_mfma_f32_16x16x32_bf16 v[130:133], v[158:161], v[176:179], v[130:133]
	v_mfma_f32_16x16x32_bf16 v[110:113], v[150:153], v[184:187], v[110:113]
	v_mfma_f32_16x16x32_bf16 v[106:109], v[158:161], v[184:187], v[106:109]
	v_mfma_f32_16x16x32_bf16 v[86:89], v[150:153], v[192:195], v[86:89]
	v_mfma_f32_16x16x32_bf16 v[82:85], v[158:161], v[192:195], v[82:85]
	v_mfma_f32_16x16x32_bf16 v[68:71], v[150:153], v[204:207], v[68:71]
	v_mfma_f32_16x16x32_bf16 v[64:67], v[158:161], v[204:207], v[64:67]
	s_setprio 0
	s_barrier
; #define PG8_STAGE(bufoff, gbase, voff) do { _Pragma("unroll") for (int _i = 0; _i < 2; ++_i) \
;         __builtin_amdgcn_global_load_lds((const unsigned*)((const char*)(gbase) + (voff)[_i]), (PG8_LAS unsigned*)(lds + (bufoff) + ldsw + _i * 8192), 16, 0, 0); } while (0)
; #define PG8_LDA(dst, b, h) do { _Pragma("unroll") for (int m = 0; m < 4; ++m) _Pragma("unroll") for (int k = 0; k < 2; ++k) dst[m][k] = *(const PG8_LAS bf16x8*)(lds + PG8_SA(b, h) + aoff + m * 2048 + k * 1024); } while (0)
; #define PG8_MMA(ai, bj, At, Bt) do { __builtin_amdgcn_s_setprio(1); _Pragma("unroll") for (int m = 0; m < 4; ++m) _Pragma("unroll") for (int n = 0; n < 2; ++n) _Pragma("unroll") for (int k = 0; k < 2; ++k) \
;         acc[ai][bj][m][n] = __builtin_amdgcn_mfma_f32_16x16x32_bf16(Bt[n][k], At[m][k], acc[ai][bj][m][n], 0, 0, 0); __builtin_amdgcn_s_setprio(0); } while (0)
; #define PG8_WAIT_V(n) asm volatile("s_waitcnt vmcnt(" #n ")" ::: "memory")
; #define PG8_WAIT_L(n) asm volatile("s_waitcnt lgkmcnt(" #n ")" ::: "memory")
; #define PG8_BAR __builtin_amdgcn_s_barrier()
; #define PG8_SCHED __builtin_amdgcn_sched_barrier(0)
; template <class Epi, class Sched, bool ALIGN_EPI = false, bool SP2 = false>
; __device__ __forceinline__ void gemm_phase(PG8_LAS unsigned char* lds, const Gemm g, const Sched& S, const Epi& E, int tid_in) {
;     ...
;             PG8_LDA(At, 1, 1); PG8_STAGE(PG8_SB(1, 0), b3, voffB); PG8_STAGE(PG8_SB(1, 1), b3 + hstep, voffB); PG8_STAGE(PG8_SA(1, 0), a3, voffA);
;             PG8_WAIT_V(8); PG8_WAIT_L(0); PG8_BAR; PG8_MMA(1, 0, At, B0); PG8_MMA(1, 1, At, B1); PG8_BAR; PG8_SCHED;
;     ...
;         if constexpr (ALIGN_EPI) { if (wr == 0) PG8_BAR; }
	s_add_i32 s2, s65, s14
	v_lshl_add_u64 v[208:209], v[208:209], 0, s[6:7]
	s_mov_b32 m0, s2
	ds_read_b128 v[172:175], v203 offset:49152
	ds_read_b128 v[176:179], v203 offset:50176
	ds_read_b128 v[180:183], v203 offset:51200
	ds_read_b128 v[184:187], v203 offset:52224
	ds_read_b128 v[188:191], v203 offset:53248
	ds_read_b128 v[192:195], v203 offset:54272
	ds_read_b128 v[196:199], v203 offset:55296
	ds_read_b128 v[204:207], v203 offset:56320
	global_load_lds_dwordx4 v[208:209], off
	s_add_i32 m0, s2, 0x2000
	s_add_u32 s2, s8, 0xb0080
	v_lshl_add_u64 v[208:209], v[210:211], 0, s[6:7]
	s_addc_u32 s3, s9, 0
	s_add_i32 s8, s77, s14
	global_load_lds_dwordx4 v[208:209], off
	v_lshl_add_u64 v[208:209], s[2:3], 0, v[80:81]
	s_mov_b32 m0, s8
	s_nop 0
	global_load_lds_dwordx4 v[208:209], off
	v_lshl_add_u64 v[208:209], s[2:3], 0, v[166:167]
	s_add_i32 m0, s8, 0x2000
	s_nop 0
	global_load_lds_dwordx4 v[208:209], off
	v_lshl_add_u64 v[208:209], v[212:213], 0, s[6:7]
	s_mov_b32 m0, s67
	s_nop 0
	global_load_lds_dwordx4 v[208:209], off
	v_lshl_add_u64 v[208:209], v[214:215], 0, s[6:7]
	s_mov_b32 m0, s68
	s_nop 0
	global_load_lds_dwordx4 v[208:209], off
	s_waitcnt vmcnt(8) lgkmcnt(0)
	s_barrier
	s_setprio 1
	v_mfma_f32_16x16x32_bf16 v[60:63], v[90:93], v[172:175], v[60:63]
	v_mfma_f32_16x16x32_bf16 v[56:59], v[114:117], v[172:175], v[56:59]
	v_mfma_f32_16x16x32_bf16 v[44:47], v[90:93], v[180:183], v[44:47]
	v_mfma_f32_16x16x32_bf16 v[40:43], v[114:117], v[180:183], v[40:43]
	v_mfma_f32_16x16x32_bf16 v[28:31], v[90:93], v[188:191], v[28:31]
	v_mfma_f32_16x16x32_bf16 v[24:27], v[114:117], v[188:191], v[24:27]
	v_mfma_f32_16x16x32_bf16 v[12:15], v[90:93], v[196:199], v[12:15]
	v_mfma_f32_16x16x32_bf16 v[8:11], v[114:117], v[196:199], v[8:11]
	v_mfma_f32_16x16x32_bf16 v[60:63], v[102:105], v[176:179], v[60:63]
	v_mfma_f32_16x16x32_bf16 v[56:59], v[126:129], v[176:179], v[56:59]
	v_mfma_f32_16x16x32_bf16 v[44:47], v[102:105], v[184:187], v[44:47]
	v_mfma_f32_16x16x32_bf16 v[40:43], v[126:129], v[184:187], v[40:43]
	v_mfma_f32_16x16x32_bf16 v[28:31], v[102:105], v[192:195], v[28:31]
	v_mfma_f32_16x16x32_bf16 v[24:27], v[126:129], v[192:195], v[24:27]
	v_mfma_f32_16x16x32_bf16 v[12:15], v[102:105], v[204:207], v[12:15]
	v_mfma_f32_16x16x32_bf16 v[8:11], v[126:129], v[204:207], v[8:11]
	v_mfma_f32_16x16x32_bf16 v[52:55], v[138:141], v[172:175], v[52:55]
	v_mfma_f32_16x16x32_bf16 v[48:51], v[154:157], v[172:175], v[48:51]
	v_mfma_f32_16x16x32_bf16 v[36:39], v[138:141], v[180:183], v[36:39]
	v_mfma_f32_16x16x32_bf16 v[32:35], v[154:157], v[180:183], v[32:35]
	v_mfma_f32_16x16x32_bf16 v[20:23], v[138:141], v[188:191], v[20:23]
	v_mfma_f32_16x16x32_bf16 v[16:19], v[154:157], v[188:191], v[16:19]
	v_mfma_f32_16x16x32_bf16 v[4:7], v[138:141], v[196:199], v[4:7]
	v_mfma_f32_16x16x32_bf16 v[0:3], v[154:157], v[196:199], v[0:3]
	v_mfma_f32_16x16x32_bf16 v[52:55], v[150:153], v[176:179], v[52:55]
	v_mfma_f32_16x16x32_bf16 v[48:51], v[158:161], v[176:179], v[48:51]
	v_mfma_f32_16x16x32_bf16 v[36:39], v[150:153], v[184:187], v[36:39]
	v_mfma_f32_16x16x32_bf16 v[32:35], v[158:161], v[184:187], v[32:35]
	v_mfma_f32_16x16x32_bf16 v[20:23], v[150:153], v[192:195], v[20:23]
	v_mfma_f32_16x16x32_bf16 v[16:19], v[158:161], v[192:195], v[16:19]
	v_mfma_f32_16x16x32_bf16 v[4:7], v[150:153], v[204:207], v[4:7]
	v_mfma_f32_16x16x32_bf16 v[0:3], v[158:161], v[204:207], v[0:3]
	s_setprio 0
	s_barrier
	s_add_i32 s43, s43, 2
	s_add_u32 s0, s0, 0x100
	s_addc_u32 s1, s1, 0
	s_cmp_gt_u32 s43, 41
	s_mov_b64 s[2:3], s[4:5]
	s_cbranch_scc0 .LBB0_1689
	s_and_b64 vcc, exec, s[58:59]
	s_cbranch_vccz .LBB0_1692
	s_barrier
